# P4 w_in GEMM epilogue: row-norm partial loads prefetched three row groups ahead with counted waits, bf16 store pairs merged to 16-byte stores
# speedup vs baseline: 1.0063x; 1.0063x over previous
.LBB0_331:
	v_lshl_add_u32 v154, s8, 8, v1
	v_ashrrev_i32_e32 v155, 31, v154
	v_lshlrev_b64 v[156:157], 6, v[154:155]
	v_lshl_add_u64 v[156:157], s[30:31], 0, v[156:157]
	v_and_b32_e32 v250, 16, v0
	v_lshrrev_b32_e32 v251, 1, v250
	v_add_u32_e32 v250, v250, v251
	v_mov_b32_e32 v251, 0
	v_mov_b32_e32 v242, v156
	v_mov_b32_e32 v243, v157
	v_mov_b32_e32 v244, 0x2000
	v_mov_b32_e32 v245, 0
	v_lshl_add_u64 v[244:245], v[156:157], 0, v[244:245]
	global_load_dwordx4 v[166:169], v[156:157], off
	global_load_dwordx4 v[170:173], v[156:157], off offset:16
	global_load_dwordx4 v[174:177], v[156:157], off offset:32
	global_load_dwordx4 v[178:181], v[156:157], off offset:48
	global_load_dwordx4 v[194:197], v[242:243], off offset:1024
	global_load_dwordx4 v[198:201], v[242:243], off offset:1040
	global_load_dwordx4 v[202:205], v[242:243], off offset:1056
	global_load_dwordx4 v[206:209], v[242:243], off offset:1072
	global_load_dwordx4 v[210:213], v[242:243], off offset:2048
	global_load_dwordx4 v[214:217], v[242:243], off offset:2064
	global_load_dwordx4 v[218:221], v[242:243], off offset:2080
	global_load_dwordx4 v[222:225], v[242:243], off offset:2096
	global_load_dwordx4 v[226:229], v[242:243], off offset:3072
	global_load_dwordx4 v[230:233], v[242:243], off offset:3088
	global_load_dwordx4 v[234:237], v[242:243], off offset:3104
	global_load_dwordx4 v[238:241], v[242:243], off offset:3120
	s_cmp_gt_i32 s18, 3
	s_cselect_b64 s[20:21], -1, 0
	s_cmp_lg_u32 s18, 4
	s_cselect_b64 s[22:23], -1, 0
	s_cmp_lt_i32 s18, 2
	s_cselect_b64 s[84:85], -1, 0
	s_cmp_gt_i32 s18, 1
	s_mov_b64 s[8:9], -1
	s_cselect_b64 s[38:39], -1, 0
	s_and_b64 vcc, exec, s[20:21]
	s_waitcnt vmcnt(12)
	v_pk_add_f32 v[156:157], v[168:169], v[172:173]
	v_pk_add_f32 v[166:167], v[166:167], v[170:171]
	v_pk_add_f32 v[168:169], v[176:177], v[180:181]
	v_pk_add_f32 v[170:171], v[174:175], v[178:179]
	v_pk_add_f32 v[156:157], v[156:157], v[168:169]
	v_pk_add_f32 v[166:167], v[166:167], v[170:171]
	s_nop 0
	v_pk_mov_b32 v[168:169], v[166:167], v[156:157] op_sel:[1,0]
	v_mov_b32_e32 v167, v157
	v_pk_add_f32 v[156:157], v[168:169], v[166:167]
	s_nop 0
	v_add_f32_e32 v134, v156, v157
	v_fmamk_f32 v134, v134, 0x3a800000, v162
	v_rsq_f32_e32 v134, v134
	s_nop 0
	v_pk_mul_f32 v[128:129], v[128:129], v[134:135] op_sel_hi:[1,0]
	v_pk_mul_f32 v[126:127], v[126:127], v[134:135] op_sel_hi:[1,0]
	v_pk_mul_f32 v[124:125], v[124:125], v[134:135] op_sel_hi:[1,0]
	v_pk_mul_f32 v[122:123], v[122:123], v[134:135] op_sel_hi:[1,0]
	v_pk_mul_f32 v[120:121], v[120:121], v[134:135] op_sel_hi:[1,0]
	v_pk_mul_f32 v[118:119], v[118:119], v[134:135] op_sel_hi:[1,0]
	v_pk_mul_f32 v[116:117], v[116:117], v[134:135] op_sel_hi:[1,0]
	v_pk_mul_f32 v[114:115], v[114:115], v[134:135] op_sel_hi:[1,0]
	s_cbranch_vccz .LBB0_343
	v_mul_f32_e32 v134, v127, v127
	v_mul_f32_e32 v156, v129, v129
	v_fmac_f32_e32 v134, v126, v126
	v_fmac_f32_e32 v156, v128, v128
	v_add_f32_e32 v166, v134, v156
	s_and_b64 vcc, exec, s[22:23]
	v_lshlrev_b64 v[156:157], 9, v[154:155]
	v_mul_f32_e32 v167, v123, v123
	v_mul_f32_e32 v168, v125, v125
	s_cbranch_vccz .LBB0_338
	v_fma_f32 v134, v122, v122, v167
	v_fma_f32 v169, v124, v124, v168
	v_and_b32_e32 v173, 64, v163
	v_add_f32_e32 v134, v134, v169
	v_xor_b32_e32 v169, 16, v163
	v_add_u32_e32 v176, 64, v173
	v_cmp_lt_i32_e32 vcc, v169, v176
	v_add_f32_e32 v134, v166, v134
	v_lshlrev_b64 v[174:175], 8, v[154:155]
	v_cndmask_b32_e32 v169, v163, v169, vcc
	v_lshlrev_b32_e32 v169, 2, v169
	ds_bpermute_b32 v169, v169, v134
	v_lshl_add_u64 v[170:171], v[140:141], 0, v[156:157]
	v_lshl_add_u64 v[174:175], v[142:143], 0, v[174:175]
	global_store_dwordx4 v[170:171], v[126:129], off
	v_cvt_pk_bf16_f32 v172, v126, v127
	s_waitcnt lgkmcnt(0)
	v_add_f32_e32 v134, v134, v169
	v_xor_b32_e32 v169, 32, v163
	v_cmp_lt_i32_e32 vcc, v169, v176
	v_cvt_pk_bf16_f32 v173, v128, v129
	global_store_dwordx2 v[174:175], v[172:173], off
	global_store_dwordx4 v[170:171], v[122:125], off offset:64
	v_cndmask_b32_e32 v169, v163, v169, vcc
	v_lshlrev_b32_e32 v169, 2, v169
	ds_bpermute_b32 v169, v169, v134
	v_cvt_pk_bf16_f32 v170, v122, v123
	v_cvt_pk_bf16_f32 v171, v124, v125
	global_store_dwordx2 v[174:175], v[170:171], off offset:32
	s_and_saveexec_b64 s[8:9], s[4:5]
	s_cbranch_execz .LBB0_335
	v_lshlrev_b64 v[170:171], 5, v[154:155]
	v_lshl_add_u64 v[170:171], s[42:43], 0, v[170:171]
	s_waitcnt lgkmcnt(0)
	v_add_f32_e32 v134, v134, v169
	global_store_dword v[170:171], v134, off offset:16

.LBB0_346:
	s_and_b64 s[0:1], s[84:85], exec
	s_cselect_b32 s1, s79, s87
	s_cselect_b32 s0, s78, s86
	s_waitcnt lgkmcnt(0)
	v_lshlrev_b64 v[156:157], 10, v[154:155]
	v_lshl_add_u64 v[156:157], s[0:1], 0, v[156:157]
	s_lshl_b32 s26, s69, 1
	v_lshl_add_u64 v[156:157], v[156:157], 0, s[26:27]
	s_lshl_b32 s26, s88, 1
	v_lshl_add_u64 v[156:157], v[156:157], 0, s[26:27]
	v_lshlrev_b32_e32 v134, 1, v136
	v_lshl_add_u64 v[156:157], v[156:157], 0, v[134:135]
	s_and_b64 vcc, exec, s[8:9]
	v_cvt_pk_bf16_f32 v126, v126, v127
	v_cvt_pk_bf16_f32 v127, v128, v129
	v_mov_b32_e32 v246, v126
	v_mov_b32_e32 v247, v127
	s_cbranch_vccnz .LBB0_348
	v_mul_f32_e32 v127, 0x3d372713, v123
	v_mov_b32_e32 v128, v123
	v_mul_f32_e32 v127, v123, v127
	v_fmac_f32_e32 v128, v128, v127
	v_mul_f32_e32 v126, 0x3d372713, v122
	v_mul_f32_e32 v127, 0x3f4c422a, v128
	v_mul_f32_e32 v128, 0x3d372713, v124
	v_mul_f32_e32 v129, 0x3d372713, v125
	v_mul_f32_e32 v126, v122, v126
	v_mul_f32_e32 v128, v124, v128
	v_mul_f32_e32 v129, v125, v129
	v_fma_f32 v126, v122, v126, v122
	v_fma_f32 v128, v124, v128, v124
	v_fma_f32 v129, v125, v129, v125
	v_mul_f32_e32 v126, 0x3f4c422a, v126
	v_mul_f32_e32 v128, 0x3f4c422a, v128
	v_mul_f32_e32 v129, 0x3f4c422a, v129
	v_mul_f32_e32 v126, 0xc038aa3b, v126
	v_mul_f32_e32 v127, 0xc038aa3b, v127
	v_mul_f32_e32 v128, 0xc038aa3b, v128
	v_mul_f32_e32 v129, 0xc038aa3b, v129
	v_exp_f32_e32 v126, v126
	v_exp_f32_e32 v127, v127
	v_exp_f32_e32 v128, v128
	v_exp_f32_e32 v129, v129
	v_add_f32_e32 v126, 1.0, v126
	v_add_f32_e32 v127, 1.0, v127
	v_add_f32_e32 v128, 1.0, v128
	v_add_f32_e32 v129, 1.0, v129
	v_rcp_f32_e32 v126, v126
	v_rcp_f32_e32 v128, v128
	v_rcp_f32_e32 v129, v129
	v_rcp_f32_e32 v127, v127
	v_pk_mul_f32 v[124:125], v[124:125], v[128:129]
	v_pk_mul_f32 v[122:123], v[122:123], v[126:127]
.LBB0_348:
	s_and_b64 vcc, exec, s[8:9]
	v_cvt_pk_bf16_f32 v122, v122, v123
	v_cvt_pk_bf16_f32 v123, v124, v125
	v_mov_b32_e32 v248, v122
	v_mov_b32_e32 v249, v123
	s_nop 1
	v_permlane16_swap_b32_e32 v246, v248
	v_permlane16_swap_b32_e32 v247, v249
	v_lshl_add_u64 v[252:253], v[156:157], 0, v[250:251]
	global_store_dwordx4 v[252:253], v[246:249], off
	s_nop 0
	s_cbranch_vccnz .LBB0_350
	v_mul_f32_e32 v123, 0x3d372713, v119
	v_mov_b32_e32 v124, v119
	v_mul_f32_e32 v123, v119, v123
	v_fmac_f32_e32 v124, v124, v123
	v_mul_f32_e32 v122, 0x3d372713, v118
	v_mul_f32_e32 v123, 0x3f4c422a, v124
	v_mul_f32_e32 v124, 0x3d372713, v120
	v_mul_f32_e32 v125, 0x3d372713, v121
	v_mul_f32_e32 v122, v118, v122
	v_mul_f32_e32 v124, v120, v124
	v_mul_f32_e32 v125, v121, v125
	v_fma_f32 v122, v118, v122, v118
	v_fma_f32 v124, v120, v124, v120
	v_fma_f32 v125, v121, v125, v121
	v_mul_f32_e32 v122, 0x3f4c422a, v122
	v_mul_f32_e32 v124, 0x3f4c422a, v124
	v_mul_f32_e32 v125, 0x3f4c422a, v125
	v_mul_f32_e32 v122, 0xc038aa3b, v122
	v_mul_f32_e32 v123, 0xc038aa3b, v123
	v_mul_f32_e32 v124, 0xc038aa3b, v124
	v_mul_f32_e32 v125, 0xc038aa3b, v125
	v_exp_f32_e32 v122, v122
	v_exp_f32_e32 v123, v123
	v_exp_f32_e32 v124, v124
	v_exp_f32_e32 v125, v125
	v_add_f32_e32 v122, 1.0, v122
	v_add_f32_e32 v123, 1.0, v123
	v_add_f32_e32 v124, 1.0, v124
	v_add_f32_e32 v125, 1.0, v125
	v_rcp_f32_e32 v122, v122
	v_rcp_f32_e32 v124, v124
	v_rcp_f32_e32 v125, v125
	v_rcp_f32_e32 v123, v123
	v_pk_mul_f32 v[120:121], v[120:121], v[124:125]
	v_pk_mul_f32 v[118:119], v[118:119], v[122:123]
.LBB0_350:
	s_and_b64 vcc, exec, s[8:9]
	v_cvt_pk_bf16_f32 v118, v118, v119
	v_cvt_pk_bf16_f32 v119, v120, v121
	v_mov_b32_e32 v246, v118
	v_mov_b32_e32 v247, v119
	s_cbranch_vccnz .LBB0_352
	v_mul_f32_e32 v119, 0x3d372713, v115
	v_mov_b32_e32 v120, v115
	v_mul_f32_e32 v119, v115, v119
	v_fmac_f32_e32 v120, v120, v119
	v_mul_f32_e32 v118, 0x3d372713, v114
	v_mul_f32_e32 v119, 0x3f4c422a, v120
	v_mul_f32_e32 v120, 0x3d372713, v116
	v_mul_f32_e32 v121, 0x3d372713, v117
	v_mul_f32_e32 v118, v114, v118
	v_mul_f32_e32 v120, v116, v120
	v_mul_f32_e32 v121, v117, v121
	v_fma_f32 v118, v114, v118, v114
	v_fma_f32 v120, v116, v120, v116
	v_fma_f32 v121, v117, v121, v117
	v_mul_f32_e32 v118, 0x3f4c422a, v118
	v_mul_f32_e32 v120, 0x3f4c422a, v120
	v_mul_f32_e32 v121, 0x3f4c422a, v121
	v_mul_f32_e32 v118, 0xc038aa3b, v118
	v_mul_f32_e32 v119, 0xc038aa3b, v119
	v_mul_f32_e32 v120, 0xc038aa3b, v120
	v_mul_f32_e32 v121, 0xc038aa3b, v121
	v_exp_f32_e32 v118, v118
	v_exp_f32_e32 v119, v119
	v_exp_f32_e32 v120, v120
	v_exp_f32_e32 v121, v121
	v_add_f32_e32 v118, 1.0, v118
	v_add_f32_e32 v119, 1.0, v119
	v_add_f32_e32 v120, 1.0, v120
	v_add_f32_e32 v121, 1.0, v121
	v_rcp_f32_e32 v118, v118
	v_rcp_f32_e32 v120, v120
	v_rcp_f32_e32 v121, v121
	v_rcp_f32_e32 v119, v119
	v_pk_mul_f32 v[116:117], v[116:117], v[120:121]
	v_pk_mul_f32 v[114:115], v[114:115], v[118:119]
.LBB0_352:
	s_nop 0
	v_cvt_pk_bf16_f32 v114, v114, v115
	v_cvt_pk_bf16_f32 v115, v116, v117
	v_mov_b32_e32 v248, v114
	v_mov_b32_e32 v249, v115
	s_nop 1
	v_permlane16_swap_b32_e32 v246, v248
	v_permlane16_swap_b32_e32 v247, v249
	v_lshl_add_u64 v[252:253], v[156:157], 0, v[250:251]
	global_store_dwordx4 v[252:253], v[246:249], off offset:256
	s_nop 0
.LBB0_353:
	v_or_b32_e32 v114, 16, v154
	v_ashrrev_i32_e32 v115, 31, v114
	v_lshlrev_b64 v[116:117], 6, v[114:115]
	v_lshl_add_u64 v[128:129], s[30:31], 0, v[116:117]
	s_waitcnt lgkmcnt(0)
	v_cndmask_b32_e64 v128, 0, 1, s[20:21]
	s_mov_b64 s[14:15], -1
	v_cmp_ne_u32_e64 s[12:13], 1, v128
	s_andn2_b64 vcc, exec, s[20:21]
	s_waitcnt vmcnt(10)
	v_pk_add_f32 v[118:119], v[196:197], v[200:201]
	v_pk_add_f32 v[116:117], v[194:195], v[198:199]
	v_pk_add_f32 v[120:121], v[204:205], v[208:209]
	v_pk_add_f32 v[122:123], v[202:203], v[206:207]
	global_load_dwordx4 v[194:197], v[244:245], off
	global_load_dwordx4 v[198:201], v[244:245], off offset:16
	global_load_dwordx4 v[202:205], v[244:245], off offset:32
	global_load_dwordx4 v[206:209], v[244:245], off offset:48
	v_pk_add_f32 v[118:119], v[118:119], v[120:121]
	v_pk_add_f32 v[116:117], v[116:117], v[122:123]
	s_nop 0
	v_pk_mov_b32 v[120:121], v[116:117], v[118:119] op_sel:[1,0]
	v_mov_b32_e32 v117, v119
	v_pk_add_f32 v[116:117], v[120:121], v[116:117]
	s_nop 0
	v_add_f32_e32 v116, v116, v117
	v_fmamk_f32 v116, v116, 0x3a800000, v162
	v_rsq_f32_e32 v116, v116
	v_cndmask_b32_e64 v117, 0, 1, s[22:23]
	v_cmp_ne_u32_e64 s[10:11], 1, v117
	v_pk_mul_f32 v[112:113], v[112:113], v[116:117] op_sel_hi:[1,0]
	v_pk_mul_f32 v[110:111], v[110:111], v[116:117] op_sel_hi:[1,0]
	v_pk_mul_f32 v[108:109], v[108:109], v[116:117] op_sel_hi:[1,0]
	v_pk_mul_f32 v[106:107], v[106:107], v[116:117] op_sel_hi:[1,0]
	v_pk_mul_f32 v[104:105], v[104:105], v[116:117] op_sel_hi:[1,0]
	v_pk_mul_f32 v[102:103], v[102:103], v[116:117] op_sel_hi:[1,0]
	v_pk_mul_f32 v[100:101], v[100:101], v[116:117] op_sel_hi:[1,0]
	v_pk_mul_f32 v[98:99], v[98:99], v[116:117] op_sel_hi:[1,0]
	s_cbranch_vccnz .LBB0_365
	v_mul_f32_e32 v116, v111, v111
	v_mul_f32_e32 v117, v113, v113
	v_fmac_f32_e32 v116, v110, v110
	v_fmac_f32_e32 v117, v112, v112
	v_add_f32_e32 v118, v116, v117
	s_and_b64 vcc, exec, s[10:11]
	v_lshlrev_b64 v[116:117], 9, v[114:115]
	v_mul_f32_e32 v119, v107, v107
	v_mul_f32_e32 v120, v109, v109
	s_cbranch_vccnz .LBB0_360
	v_fma_f32 v121, v106, v106, v119
	v_fma_f32 v123, v108, v108, v120
	v_and_b32_e32 v126, 64, v163
	v_add_f32_e32 v121, v121, v123
	v_xor_b32_e32 v123, 16, v163
	v_add_u32_e32 v128, 64, v126
	v_cmp_lt_i32_e32 vcc, v123, v128
	v_add_f32_e32 v121, v118, v121
	v_lshl_add_u64 v[124:125], v[140:141], 0, v[116:117]
	v_cndmask_b32_e32 v123, v163, v123, vcc
	v_lshlrev_b32_e32 v123, 2, v123
	ds_bpermute_b32 v129, v123, v121
	v_lshlrev_b64 v[126:127], 8, v[114:115]
	global_store_dwordx4 v[124:125], v[110:113], off
	v_cvt_pk_bf16_f32 v122, v110, v111
	v_lshl_add_u64 v[126:127], v[142:143], 0, v[126:127]
	v_cvt_pk_bf16_f32 v123, v112, v113
	global_store_dwordx2 v[126:127], v[122:123], off
	v_xor_b32_e32 v122, 32, v163
	v_cmp_lt_i32_e32 vcc, v122, v128
	s_waitcnt lgkmcnt(0)
	v_add_f32_e32 v121, v121, v129
	global_store_dwordx4 v[124:125], v[106:109], off offset:64
	v_cndmask_b32_e32 v122, v163, v122, vcc
	v_lshlrev_b32_e32 v122, 2, v122
	ds_bpermute_b32 v122, v122, v121
	v_cvt_pk_bf16_f32 v124, v106, v107
	v_cvt_pk_bf16_f32 v125, v108, v109
	global_store_dwordx2 v[126:127], v[124:125], off offset:32
	s_and_saveexec_b64 s[14:15], s[4:5]
	s_cbranch_execz .LBB0_357
	v_lshlrev_b64 v[124:125], 5, v[114:115]
	v_lshl_add_u64 v[124:125], s[42:43], 0, v[124:125]
	s_waitcnt lgkmcnt(0)
	v_add_f32_e32 v121, v121, v122
	global_store_dword v[124:125], v121, off offset:16

.LBB0_368:
	s_and_b64 s[0:1], s[84:85], exec
	s_cselect_b32 s1, s79, s87
	s_cselect_b32 s0, s78, s86
	v_lshlrev_b64 v[114:115], 10, v[114:115]
	v_lshl_add_u64 v[114:115], s[0:1], 0, v[114:115]
	s_lshl_b32 s26, s69, 1
	v_lshl_add_u64 v[114:115], v[114:115], 0, s[26:27]
	s_lshl_b32 s26, s88, 1
	v_lshl_add_u64 v[114:115], v[114:115], 0, s[26:27]
	v_lshlrev_b32_e32 v134, 1, v136
	v_lshl_add_u64 v[114:115], v[114:115], 0, v[134:135]
	s_and_b64 vcc, exec, s[8:9]
	v_cvt_pk_bf16_f32 v110, v110, v111
	v_cvt_pk_bf16_f32 v111, v112, v113
	v_mov_b32_e32 v246, v110
	v_mov_b32_e32 v247, v111
	s_cbranch_vccnz .LBB0_370
	v_mul_f32_e32 v111, 0x3d372713, v107
	v_mov_b32_e32 v112, v107
	v_mul_f32_e32 v111, v107, v111
	v_fmac_f32_e32 v112, v112, v111
	v_mul_f32_e32 v110, 0x3d372713, v106
	v_mul_f32_e32 v111, 0x3f4c422a, v112
	v_mul_f32_e32 v112, 0x3d372713, v108
	v_mul_f32_e32 v113, 0x3d372713, v109
	v_mul_f32_e32 v110, v106, v110
	v_mul_f32_e32 v112, v108, v112
	v_mul_f32_e32 v113, v109, v113
	v_fma_f32 v110, v106, v110, v106
	v_fma_f32 v112, v108, v112, v108
	v_fma_f32 v113, v109, v113, v109
	v_mul_f32_e32 v110, 0x3f4c422a, v110
	v_mul_f32_e32 v112, 0x3f4c422a, v112
	v_mul_f32_e32 v113, 0x3f4c422a, v113
	v_mul_f32_e32 v110, 0xc038aa3b, v110
	v_mul_f32_e32 v111, 0xc038aa3b, v111
	v_mul_f32_e32 v112, 0xc038aa3b, v112
	v_mul_f32_e32 v113, 0xc038aa3b, v113
	v_exp_f32_e32 v110, v110
	v_exp_f32_e32 v111, v111
	v_exp_f32_e32 v112, v112
	v_exp_f32_e32 v113, v113
	v_add_f32_e32 v110, 1.0, v110
	v_add_f32_e32 v111, 1.0, v111
	v_add_f32_e32 v112, 1.0, v112
	v_add_f32_e32 v113, 1.0, v113
	v_rcp_f32_e32 v110, v110
	v_rcp_f32_e32 v112, v112
	v_rcp_f32_e32 v113, v113
	v_rcp_f32_e32 v111, v111
	v_pk_mul_f32 v[108:109], v[108:109], v[112:113]
	v_pk_mul_f32 v[106:107], v[106:107], v[110:111]
.LBB0_370:
	s_and_b64 vcc, exec, s[8:9]
	v_cvt_pk_bf16_f32 v106, v106, v107
	v_cvt_pk_bf16_f32 v107, v108, v109
	v_mov_b32_e32 v248, v106
	v_mov_b32_e32 v249, v107
	s_nop 1
	v_permlane16_swap_b32_e32 v246, v248
	v_permlane16_swap_b32_e32 v247, v249
	v_lshl_add_u64 v[252:253], v[114:115], 0, v[250:251]
	global_store_dwordx4 v[252:253], v[246:249], off
	s_nop 0
	s_cbranch_vccnz .LBB0_372
	v_mul_f32_e32 v107, 0x3d372713, v103
	v_mov_b32_e32 v108, v103
	v_mul_f32_e32 v107, v103, v107
	v_fmac_f32_e32 v108, v108, v107
	v_mul_f32_e32 v106, 0x3d372713, v102
	v_mul_f32_e32 v107, 0x3f4c422a, v108
	v_mul_f32_e32 v108, 0x3d372713, v104
	v_mul_f32_e32 v109, 0x3d372713, v105
	v_mul_f32_e32 v106, v102, v106
	v_mul_f32_e32 v108, v104, v108
	v_mul_f32_e32 v109, v105, v109
	v_fma_f32 v106, v102, v106, v102
	v_fma_f32 v108, v104, v108, v104
	v_fma_f32 v109, v105, v109, v105
	v_mul_f32_e32 v106, 0x3f4c422a, v106
	v_mul_f32_e32 v108, 0x3f4c422a, v108
	v_mul_f32_e32 v109, 0x3f4c422a, v109
	v_mul_f32_e32 v106, 0xc038aa3b, v106
	v_mul_f32_e32 v107, 0xc038aa3b, v107
	v_mul_f32_e32 v108, 0xc038aa3b, v108
	v_mul_f32_e32 v109, 0xc038aa3b, v109
	v_exp_f32_e32 v106, v106
	v_exp_f32_e32 v107, v107
	v_exp_f32_e32 v108, v108
	v_exp_f32_e32 v109, v109
	v_add_f32_e32 v106, 1.0, v106
	v_add_f32_e32 v107, 1.0, v107
	v_add_f32_e32 v108, 1.0, v108
	v_add_f32_e32 v109, 1.0, v109
	v_rcp_f32_e32 v106, v106
	v_rcp_f32_e32 v108, v108
	v_rcp_f32_e32 v109, v109
	v_rcp_f32_e32 v107, v107
	v_pk_mul_f32 v[104:105], v[104:105], v[108:109]
	v_pk_mul_f32 v[102:103], v[102:103], v[106:107]
.LBB0_372:
	s_and_b64 vcc, exec, s[8:9]
	v_cvt_pk_bf16_f32 v102, v102, v103
	v_cvt_pk_bf16_f32 v103, v104, v105
	v_mov_b32_e32 v246, v102
	v_mov_b32_e32 v247, v103
	s_cbranch_vccnz .LBB0_374
	v_mul_f32_e32 v103, 0x3d372713, v99
	v_mov_b32_e32 v104, v99
	v_mul_f32_e32 v103, v99, v103
	v_fmac_f32_e32 v104, v104, v103
	v_mul_f32_e32 v102, 0x3d372713, v98
	v_mul_f32_e32 v103, 0x3f4c422a, v104
	v_mul_f32_e32 v104, 0x3d372713, v100
	v_mul_f32_e32 v105, 0x3d372713, v101
	v_mul_f32_e32 v102, v98, v102
	v_mul_f32_e32 v104, v100, v104
	v_mul_f32_e32 v105, v101, v105
	v_fma_f32 v102, v98, v102, v98
	v_fma_f32 v104, v100, v104, v100
	v_fma_f32 v105, v101, v105, v101
	v_mul_f32_e32 v102, 0x3f4c422a, v102
	v_mul_f32_e32 v104, 0x3f4c422a, v104
	v_mul_f32_e32 v105, 0x3f4c422a, v105
	v_mul_f32_e32 v102, 0xc038aa3b, v102
	v_mul_f32_e32 v103, 0xc038aa3b, v103
	v_mul_f32_e32 v104, 0xc038aa3b, v104
	v_mul_f32_e32 v105, 0xc038aa3b, v105
	v_exp_f32_e32 v102, v102
	v_exp_f32_e32 v103, v103
	v_exp_f32_e32 v104, v104
	v_exp_f32_e32 v105, v105
	v_add_f32_e32 v102, 1.0, v102
	v_add_f32_e32 v103, 1.0, v103
	v_add_f32_e32 v104, 1.0, v104
	v_add_f32_e32 v105, 1.0, v105
	v_rcp_f32_e32 v102, v102
	v_rcp_f32_e32 v104, v104
	v_rcp_f32_e32 v105, v105
	v_rcp_f32_e32 v103, v103
	v_pk_mul_f32 v[100:101], v[100:101], v[104:105]
	v_pk_mul_f32 v[98:99], v[98:99], v[102:103]
.LBB0_374:
	s_nop 0
	v_cvt_pk_bf16_f32 v98, v98, v99
	v_cvt_pk_bf16_f32 v99, v100, v101
	v_mov_b32_e32 v248, v98
	v_mov_b32_e32 v249, v99
	s_nop 1
	v_permlane16_swap_b32_e32 v246, v248
	v_permlane16_swap_b32_e32 v247, v249
	v_lshl_add_u64 v[252:253], v[114:115], 0, v[250:251]
	global_store_dwordx4 v[252:253], v[246:249], off offset:256
	s_nop 0
.LBB0_375:
	v_or_b32_e32 v98, 32, v154
	v_ashrrev_i32_e32 v99, 31, v98
	v_lshlrev_b64 v[100:101], 6, v[98:99]
	v_lshl_add_u64 v[112:113], s[30:31], 0, v[100:101]
	s_nop 0
	s_and_b64 vcc, exec, s[12:13]
	s_mov_b64 s[14:15], -1
	s_waitcnt vmcnt(12)
	v_pk_add_f32 v[102:103], v[212:213], v[216:217]
	v_pk_add_f32 v[100:101], v[210:211], v[214:215]
	v_pk_add_f32 v[104:105], v[220:221], v[224:225]
	v_pk_add_f32 v[106:107], v[218:219], v[222:223]
	global_load_dwordx4 v[210:213], v[244:245], off offset:1024
	global_load_dwordx4 v[214:217], v[244:245], off offset:1040
	global_load_dwordx4 v[218:221], v[244:245], off offset:1056
	global_load_dwordx4 v[222:225], v[244:245], off offset:1072
	v_pk_add_f32 v[102:103], v[102:103], v[104:105]
	v_pk_add_f32 v[100:101], v[100:101], v[106:107]
	s_nop 0
	v_pk_mov_b32 v[104:105], v[100:101], v[102:103] op_sel:[1,0]
	v_mov_b32_e32 v101, v103
	v_pk_add_f32 v[100:101], v[104:105], v[100:101]
	s_nop 0
	v_add_f32_e32 v100, v100, v101
	v_fmamk_f32 v100, v100, 0x3a800000, v162
	v_rsq_f32_e32 v100, v100
	s_nop 0
	v_pk_mul_f32 v[96:97], v[96:97], v[100:101] op_sel_hi:[1,0]
	v_pk_mul_f32 v[94:95], v[94:95], v[100:101] op_sel_hi:[1,0]
	v_pk_mul_f32 v[92:93], v[92:93], v[100:101] op_sel_hi:[1,0]
	v_pk_mul_f32 v[90:91], v[90:91], v[100:101] op_sel_hi:[1,0]
	v_pk_mul_f32 v[88:89], v[88:89], v[100:101] op_sel_hi:[1,0]
	v_pk_mul_f32 v[86:87], v[86:87], v[100:101] op_sel_hi:[1,0]
	v_pk_mul_f32 v[84:85], v[84:85], v[100:101] op_sel_hi:[1,0]
	v_pk_mul_f32 v[82:83], v[82:83], v[100:101] op_sel_hi:[1,0]
	s_cbranch_vccnz .LBB0_387
	v_mul_f32_e32 v100, v95, v95
	v_mul_f32_e32 v101, v97, v97
	v_fmac_f32_e32 v100, v94, v94
	v_fmac_f32_e32 v101, v96, v96
	v_add_f32_e32 v102, v100, v101
	s_and_b64 vcc, exec, s[10:11]
	v_lshlrev_b64 v[100:101], 9, v[98:99]
	v_mul_f32_e32 v103, v91, v91
	v_mul_f32_e32 v104, v93, v93
	s_cbranch_vccnz .LBB0_382
	v_fma_f32 v105, v90, v90, v103
	v_fma_f32 v107, v92, v92, v104
	v_and_b32_e32 v110, 64, v163
	v_add_f32_e32 v105, v105, v107
	v_xor_b32_e32 v107, 16, v163
	v_add_u32_e32 v112, 64, v110
	v_cmp_lt_i32_e32 vcc, v107, v112
	v_add_f32_e32 v105, v102, v105
	v_lshl_add_u64 v[108:109], v[140:141], 0, v[100:101]
	v_cndmask_b32_e32 v107, v163, v107, vcc
	v_lshlrev_b32_e32 v107, 2, v107
	ds_bpermute_b32 v113, v107, v105
	v_lshlrev_b64 v[110:111], 8, v[98:99]
	global_store_dwordx4 v[108:109], v[94:97], off
	v_cvt_pk_bf16_f32 v106, v94, v95
	v_lshl_add_u64 v[110:111], v[142:143], 0, v[110:111]
	v_cvt_pk_bf16_f32 v107, v96, v97
	global_store_dwordx2 v[110:111], v[106:107], off
	v_xor_b32_e32 v106, 32, v163
	v_cmp_lt_i32_e32 vcc, v106, v112
	s_waitcnt lgkmcnt(0)
	v_add_f32_e32 v105, v105, v113
	global_store_dwordx4 v[108:109], v[90:93], off offset:64
	v_cndmask_b32_e32 v106, v163, v106, vcc
	v_lshlrev_b32_e32 v106, 2, v106
	ds_bpermute_b32 v106, v106, v105
	v_cvt_pk_bf16_f32 v108, v90, v91
	v_cvt_pk_bf16_f32 v109, v92, v93
	global_store_dwordx2 v[110:111], v[108:109], off offset:32
	s_and_saveexec_b64 s[14:15], s[4:5]
	s_cbranch_execz .LBB0_379
	v_lshlrev_b64 v[108:109], 5, v[98:99]
	v_lshl_add_u64 v[108:109], s[42:43], 0, v[108:109]
	s_waitcnt lgkmcnt(0)
	v_add_f32_e32 v105, v105, v106
	global_store_dword v[108:109], v105, off offset:16

.LBB0_390:
	s_and_b64 s[0:1], s[84:85], exec
	s_cselect_b32 s1, s79, s87
	s_cselect_b32 s0, s78, s86
	v_lshlrev_b64 v[98:99], 10, v[98:99]
	v_lshl_add_u64 v[98:99], s[0:1], 0, v[98:99]
	s_lshl_b32 s26, s69, 1
	v_lshl_add_u64 v[98:99], v[98:99], 0, s[26:27]
	s_lshl_b32 s26, s88, 1
	v_lshl_add_u64 v[98:99], v[98:99], 0, s[26:27]
	v_lshlrev_b32_e32 v134, 1, v136
	v_lshl_add_u64 v[98:99], v[98:99], 0, v[134:135]
	s_and_b64 vcc, exec, s[8:9]
	v_cvt_pk_bf16_f32 v94, v94, v95
	v_cvt_pk_bf16_f32 v95, v96, v97
	v_mov_b32_e32 v246, v94
	v_mov_b32_e32 v247, v95
	s_cbranch_vccnz .LBB0_392
	v_mul_f32_e32 v95, 0x3d372713, v91
	v_mov_b32_e32 v96, v91
	v_mul_f32_e32 v95, v91, v95
	v_fmac_f32_e32 v96, v96, v95
	v_mul_f32_e32 v94, 0x3d372713, v90
	v_mul_f32_e32 v95, 0x3f4c422a, v96
	v_mul_f32_e32 v96, 0x3d372713, v92
	v_mul_f32_e32 v97, 0x3d372713, v93
	v_mul_f32_e32 v94, v90, v94
	v_mul_f32_e32 v96, v92, v96
	v_mul_f32_e32 v97, v93, v97
	v_fma_f32 v94, v90, v94, v90
	v_fma_f32 v96, v92, v96, v92
	v_fma_f32 v97, v93, v97, v93
	v_mul_f32_e32 v94, 0x3f4c422a, v94
	v_mul_f32_e32 v96, 0x3f4c422a, v96
	v_mul_f32_e32 v97, 0x3f4c422a, v97
	v_mul_f32_e32 v94, 0xc038aa3b, v94
	v_mul_f32_e32 v95, 0xc038aa3b, v95
	v_mul_f32_e32 v96, 0xc038aa3b, v96
	v_mul_f32_e32 v97, 0xc038aa3b, v97
	v_exp_f32_e32 v94, v94
	v_exp_f32_e32 v95, v95
	v_exp_f32_e32 v96, v96
	v_exp_f32_e32 v97, v97
	v_add_f32_e32 v94, 1.0, v94
	v_add_f32_e32 v95, 1.0, v95
	v_add_f32_e32 v96, 1.0, v96
	v_add_f32_e32 v97, 1.0, v97
	v_rcp_f32_e32 v94, v94
	v_rcp_f32_e32 v96, v96
	v_rcp_f32_e32 v97, v97
	v_rcp_f32_e32 v95, v95
	v_pk_mul_f32 v[92:93], v[92:93], v[96:97]
	v_pk_mul_f32 v[90:91], v[90:91], v[94:95]
.LBB0_392:
	s_and_b64 vcc, exec, s[8:9]
	v_cvt_pk_bf16_f32 v90, v90, v91
	v_cvt_pk_bf16_f32 v91, v92, v93
	v_mov_b32_e32 v248, v90
	v_mov_b32_e32 v249, v91
	s_nop 1
	v_permlane16_swap_b32_e32 v246, v248
	v_permlane16_swap_b32_e32 v247, v249
	v_lshl_add_u64 v[252:253], v[98:99], 0, v[250:251]
	global_store_dwordx4 v[252:253], v[246:249], off
	s_nop 0
	s_cbranch_vccnz .LBB0_394
	v_mul_f32_e32 v91, 0x3d372713, v87
	v_mov_b32_e32 v92, v87
	v_mul_f32_e32 v91, v87, v91
	v_fmac_f32_e32 v92, v92, v91
	v_mul_f32_e32 v90, 0x3d372713, v86
	v_mul_f32_e32 v91, 0x3f4c422a, v92
	v_mul_f32_e32 v92, 0x3d372713, v88
	v_mul_f32_e32 v93, 0x3d372713, v89
	v_mul_f32_e32 v90, v86, v90
	v_mul_f32_e32 v92, v88, v92
	v_mul_f32_e32 v93, v89, v93
	v_fma_f32 v90, v86, v90, v86
	v_fma_f32 v92, v88, v92, v88
	v_fma_f32 v93, v89, v93, v89
	v_mul_f32_e32 v90, 0x3f4c422a, v90
	v_mul_f32_e32 v92, 0x3f4c422a, v92
	v_mul_f32_e32 v93, 0x3f4c422a, v93
	v_mul_f32_e32 v90, 0xc038aa3b, v90
	v_mul_f32_e32 v91, 0xc038aa3b, v91
	v_mul_f32_e32 v92, 0xc038aa3b, v92
	v_mul_f32_e32 v93, 0xc038aa3b, v93
	v_exp_f32_e32 v90, v90
	v_exp_f32_e32 v91, v91
	v_exp_f32_e32 v92, v92
	v_exp_f32_e32 v93, v93
	v_add_f32_e32 v90, 1.0, v90
	v_add_f32_e32 v91, 1.0, v91
	v_add_f32_e32 v92, 1.0, v92
	v_add_f32_e32 v93, 1.0, v93
	v_rcp_f32_e32 v90, v90
	v_rcp_f32_e32 v92, v92
	v_rcp_f32_e32 v93, v93
	v_rcp_f32_e32 v91, v91
	v_pk_mul_f32 v[88:89], v[88:89], v[92:93]
	v_pk_mul_f32 v[86:87], v[86:87], v[90:91]
.LBB0_394:
	s_and_b64 vcc, exec, s[8:9]
	v_cvt_pk_bf16_f32 v86, v86, v87
	v_cvt_pk_bf16_f32 v87, v88, v89
	v_mov_b32_e32 v246, v86
	v_mov_b32_e32 v247, v87
	s_cbranch_vccnz .LBB0_396
	v_mul_f32_e32 v87, 0x3d372713, v83
	v_mov_b32_e32 v88, v83
	v_mul_f32_e32 v87, v83, v87
	v_fmac_f32_e32 v88, v88, v87
	v_mul_f32_e32 v86, 0x3d372713, v82
	v_mul_f32_e32 v87, 0x3f4c422a, v88
	v_mul_f32_e32 v88, 0x3d372713, v84
	v_mul_f32_e32 v89, 0x3d372713, v85
	v_mul_f32_e32 v86, v82, v86
	v_mul_f32_e32 v88, v84, v88
	v_mul_f32_e32 v89, v85, v89
	v_fma_f32 v86, v82, v86, v82
	v_fma_f32 v88, v84, v88, v84
	v_fma_f32 v89, v85, v89, v85
	v_mul_f32_e32 v86, 0x3f4c422a, v86
	v_mul_f32_e32 v88, 0x3f4c422a, v88
	v_mul_f32_e32 v89, 0x3f4c422a, v89
	v_mul_f32_e32 v86, 0xc038aa3b, v86
	v_mul_f32_e32 v87, 0xc038aa3b, v87
	v_mul_f32_e32 v88, 0xc038aa3b, v88
	v_mul_f32_e32 v89, 0xc038aa3b, v89
	v_exp_f32_e32 v86, v86
	v_exp_f32_e32 v87, v87
	v_exp_f32_e32 v88, v88
	v_exp_f32_e32 v89, v89
	v_add_f32_e32 v86, 1.0, v86
	v_add_f32_e32 v87, 1.0, v87
	v_add_f32_e32 v88, 1.0, v88
	v_add_f32_e32 v89, 1.0, v89
	v_rcp_f32_e32 v86, v86
	v_rcp_f32_e32 v88, v88
	v_rcp_f32_e32 v89, v89
	v_rcp_f32_e32 v87, v87
	v_pk_mul_f32 v[84:85], v[84:85], v[88:89]
	v_pk_mul_f32 v[82:83], v[82:83], v[86:87]
.LBB0_396:
	s_nop 0
	v_cvt_pk_bf16_f32 v82, v82, v83
	v_cvt_pk_bf16_f32 v83, v84, v85
	v_mov_b32_e32 v248, v82
	v_mov_b32_e32 v249, v83
	s_nop 1
	v_permlane16_swap_b32_e32 v246, v248
	v_permlane16_swap_b32_e32 v247, v249
	v_lshl_add_u64 v[252:253], v[98:99], 0, v[250:251]
	global_store_dwordx4 v[252:253], v[246:249], off offset:256
	s_nop 0
.LBB0_397:
	v_or_b32_e32 v82, 48, v154
	v_ashrrev_i32_e32 v83, 31, v82
	v_lshlrev_b64 v[84:85], 6, v[82:83]
	v_lshl_add_u64 v[96:97], s[30:31], 0, v[84:85]
	s_nop 0
	s_and_b64 vcc, exec, s[12:13]
	s_mov_b64 s[14:15], -1
	s_waitcnt vmcnt(14)
	v_pk_add_f32 v[86:87], v[228:229], v[232:233]
	v_pk_add_f32 v[84:85], v[226:227], v[230:231]
	v_pk_add_f32 v[88:89], v[236:237], v[240:241]
	v_pk_add_f32 v[90:91], v[234:235], v[238:239]
	global_load_dwordx4 v[226:229], v[244:245], off offset:2048
	global_load_dwordx4 v[230:233], v[244:245], off offset:2064
	global_load_dwordx4 v[234:237], v[244:245], off offset:2080
	global_load_dwordx4 v[238:241], v[244:245], off offset:2096
	v_pk_add_f32 v[86:87], v[86:87], v[88:89]
	v_pk_add_f32 v[84:85], v[84:85], v[90:91]
	s_nop 0
	v_pk_mov_b32 v[88:89], v[84:85], v[86:87] op_sel:[1,0]
	v_mov_b32_e32 v85, v87
	v_pk_add_f32 v[84:85], v[88:89], v[84:85]
	s_nop 0
	v_add_f32_e32 v84, v84, v85
	v_fmamk_f32 v84, v84, 0x3a800000, v162
	v_rsq_f32_e32 v84, v84
	s_nop 0
	v_pk_mul_f32 v[80:81], v[80:81], v[84:85] op_sel_hi:[1,0]
	v_pk_mul_f32 v[78:79], v[78:79], v[84:85] op_sel_hi:[1,0]
	v_pk_mul_f32 v[76:77], v[76:77], v[84:85] op_sel_hi:[1,0]
	v_pk_mul_f32 v[74:75], v[74:75], v[84:85] op_sel_hi:[1,0]
	v_pk_mul_f32 v[72:73], v[72:73], v[84:85] op_sel_hi:[1,0]
	v_pk_mul_f32 v[70:71], v[70:71], v[84:85] op_sel_hi:[1,0]
	v_pk_mul_f32 v[68:69], v[68:69], v[84:85] op_sel_hi:[1,0]
	v_pk_mul_f32 v[66:67], v[66:67], v[84:85] op_sel_hi:[1,0]
	s_cbranch_vccnz .LBB0_409
	v_mul_f32_e32 v84, v79, v79
	v_mul_f32_e32 v85, v81, v81
	v_fmac_f32_e32 v84, v78, v78
	v_fmac_f32_e32 v85, v80, v80
	v_add_f32_e32 v86, v84, v85
	s_and_b64 vcc, exec, s[10:11]
	v_lshlrev_b64 v[84:85], 9, v[82:83]
	v_mul_f32_e32 v87, v75, v75
	v_mul_f32_e32 v88, v77, v77
	s_cbranch_vccnz .LBB0_404
	v_fma_f32 v89, v74, v74, v87
	v_fma_f32 v91, v76, v76, v88
	v_and_b32_e32 v94, 64, v163
	v_add_f32_e32 v89, v89, v91
	v_xor_b32_e32 v91, 16, v163
	v_add_u32_e32 v96, 64, v94
	v_cmp_lt_i32_e32 vcc, v91, v96
	v_add_f32_e32 v89, v86, v89
	v_lshl_add_u64 v[92:93], v[140:141], 0, v[84:85]
	v_cndmask_b32_e32 v91, v163, v91, vcc
	v_lshlrev_b32_e32 v91, 2, v91
	ds_bpermute_b32 v97, v91, v89
	v_lshlrev_b64 v[94:95], 8, v[82:83]
	global_store_dwordx4 v[92:93], v[78:81], off
	v_cvt_pk_bf16_f32 v90, v78, v79
	v_lshl_add_u64 v[94:95], v[142:143], 0, v[94:95]
	v_cvt_pk_bf16_f32 v91, v80, v81
	global_store_dwordx2 v[94:95], v[90:91], off
	v_xor_b32_e32 v90, 32, v163
	v_cmp_lt_i32_e32 vcc, v90, v96
	s_waitcnt lgkmcnt(0)
	v_add_f32_e32 v89, v89, v97
	global_store_dwordx4 v[92:93], v[74:77], off offset:64
	v_cndmask_b32_e32 v90, v163, v90, vcc
	v_lshlrev_b32_e32 v90, 2, v90
	ds_bpermute_b32 v90, v90, v89
	v_cvt_pk_bf16_f32 v92, v74, v75
	v_cvt_pk_bf16_f32 v93, v76, v77
	global_store_dwordx2 v[94:95], v[92:93], off offset:32
	s_and_saveexec_b64 s[14:15], s[4:5]
	s_cbranch_execz .LBB0_401
	v_lshlrev_b64 v[92:93], 5, v[82:83]
	v_lshl_add_u64 v[92:93], s[42:43], 0, v[92:93]
	s_waitcnt lgkmcnt(0)
	v_add_f32_e32 v89, v89, v90
	global_store_dword v[92:93], v89, off offset:16

.LBB0_412:
	s_and_b64 s[0:1], s[84:85], exec
	s_cselect_b32 s1, s79, s87
	s_cselect_b32 s0, s78, s86
	v_lshlrev_b64 v[82:83], 10, v[82:83]
	v_lshl_add_u64 v[82:83], s[0:1], 0, v[82:83]
	s_lshl_b32 s26, s69, 1
	v_lshl_add_u64 v[82:83], v[82:83], 0, s[26:27]
	s_lshl_b32 s26, s88, 1
	v_lshl_add_u64 v[82:83], v[82:83], 0, s[26:27]
	v_lshlrev_b32_e32 v134, 1, v136
	v_lshl_add_u64 v[82:83], v[82:83], 0, v[134:135]
	s_and_b64 vcc, exec, s[8:9]
	v_cvt_pk_bf16_f32 v78, v78, v79
	v_cvt_pk_bf16_f32 v79, v80, v81
	v_mov_b32_e32 v246, v78
	v_mov_b32_e32 v247, v79
	s_cbranch_vccnz .LBB0_414
	v_mul_f32_e32 v79, 0x3d372713, v75
	v_mov_b32_e32 v80, v75
	v_mul_f32_e32 v79, v75, v79
	v_fmac_f32_e32 v80, v80, v79
	v_mul_f32_e32 v78, 0x3d372713, v74
	v_mul_f32_e32 v79, 0x3f4c422a, v80
	v_mul_f32_e32 v80, 0x3d372713, v76
	v_mul_f32_e32 v81, 0x3d372713, v77
	v_mul_f32_e32 v78, v74, v78
	v_mul_f32_e32 v80, v76, v80
	v_mul_f32_e32 v81, v77, v81
	v_fma_f32 v78, v74, v78, v74
	v_fma_f32 v80, v76, v80, v76
	v_fma_f32 v81, v77, v81, v77
	v_mul_f32_e32 v78, 0x3f4c422a, v78
	v_mul_f32_e32 v80, 0x3f4c422a, v80
	v_mul_f32_e32 v81, 0x3f4c422a, v81
	v_mul_f32_e32 v78, 0xc038aa3b, v78
	v_mul_f32_e32 v79, 0xc038aa3b, v79
	v_mul_f32_e32 v80, 0xc038aa3b, v80
	v_mul_f32_e32 v81, 0xc038aa3b, v81
	v_exp_f32_e32 v78, v78
	v_exp_f32_e32 v79, v79
	v_exp_f32_e32 v80, v80
	v_exp_f32_e32 v81, v81
	v_add_f32_e32 v78, 1.0, v78
	v_add_f32_e32 v79, 1.0, v79
	v_add_f32_e32 v80, 1.0, v80
	v_add_f32_e32 v81, 1.0, v81
	v_rcp_f32_e32 v78, v78
	v_rcp_f32_e32 v80, v80
	v_rcp_f32_e32 v81, v81
	v_rcp_f32_e32 v79, v79
	v_pk_mul_f32 v[76:77], v[76:77], v[80:81]
	v_pk_mul_f32 v[74:75], v[74:75], v[78:79]
.LBB0_414:
	s_and_b64 vcc, exec, s[8:9]
	v_cvt_pk_bf16_f32 v74, v74, v75
	v_cvt_pk_bf16_f32 v75, v76, v77
	v_mov_b32_e32 v248, v74
	v_mov_b32_e32 v249, v75
	s_nop 1
	v_permlane16_swap_b32_e32 v246, v248
	v_permlane16_swap_b32_e32 v247, v249
	v_lshl_add_u64 v[252:253], v[82:83], 0, v[250:251]
	global_store_dwordx4 v[252:253], v[246:249], off
	s_nop 0
	s_cbranch_vccnz .LBB0_416
	v_mul_f32_e32 v75, 0x3d372713, v71
	v_mov_b32_e32 v76, v71
	v_mul_f32_e32 v75, v71, v75
	v_fmac_f32_e32 v76, v76, v75
	v_mul_f32_e32 v74, 0x3d372713, v70
	v_mul_f32_e32 v75, 0x3f4c422a, v76
	v_mul_f32_e32 v76, 0x3d372713, v72
	v_mul_f32_e32 v77, 0x3d372713, v73
	v_mul_f32_e32 v74, v70, v74
	v_mul_f32_e32 v76, v72, v76
	v_mul_f32_e32 v77, v73, v77
	v_fma_f32 v74, v70, v74, v70
	v_fma_f32 v76, v72, v76, v72
	v_fma_f32 v77, v73, v77, v73
	v_mul_f32_e32 v74, 0x3f4c422a, v74
	v_mul_f32_e32 v76, 0x3f4c422a, v76
	v_mul_f32_e32 v77, 0x3f4c422a, v77
	v_mul_f32_e32 v74, 0xc038aa3b, v74
	v_mul_f32_e32 v75, 0xc038aa3b, v75
	v_mul_f32_e32 v76, 0xc038aa3b, v76
	v_mul_f32_e32 v77, 0xc038aa3b, v77
	v_exp_f32_e32 v74, v74
	v_exp_f32_e32 v75, v75
	v_exp_f32_e32 v76, v76
	v_exp_f32_e32 v77, v77
	v_add_f32_e32 v74, 1.0, v74
	v_add_f32_e32 v75, 1.0, v75
	v_add_f32_e32 v76, 1.0, v76
	v_add_f32_e32 v77, 1.0, v77
	v_rcp_f32_e32 v74, v74
	v_rcp_f32_e32 v76, v76
	v_rcp_f32_e32 v77, v77
	v_rcp_f32_e32 v75, v75
	v_pk_mul_f32 v[72:73], v[72:73], v[76:77]
	v_pk_mul_f32 v[70:71], v[70:71], v[74:75]
.LBB0_416:
	s_and_b64 vcc, exec, s[8:9]
	v_cvt_pk_bf16_f32 v70, v70, v71
	v_cvt_pk_bf16_f32 v71, v72, v73
	v_mov_b32_e32 v246, v70
	v_mov_b32_e32 v247, v71
	s_cbranch_vccnz .LBB0_418
	v_mul_f32_e32 v71, 0x3d372713, v67
	v_mov_b32_e32 v72, v67
	v_mul_f32_e32 v71, v67, v71
	v_fmac_f32_e32 v72, v72, v71
	v_mul_f32_e32 v70, 0x3d372713, v66
	v_mul_f32_e32 v71, 0x3f4c422a, v72
	v_mul_f32_e32 v72, 0x3d372713, v68
	v_mul_f32_e32 v73, 0x3d372713, v69
	v_mul_f32_e32 v70, v66, v70
	v_mul_f32_e32 v72, v68, v72
	v_mul_f32_e32 v73, v69, v73
	v_fma_f32 v70, v66, v70, v66
	v_fma_f32 v72, v68, v72, v68
	v_fma_f32 v73, v69, v73, v69
	v_mul_f32_e32 v70, 0x3f4c422a, v70
	v_mul_f32_e32 v72, 0x3f4c422a, v72
	v_mul_f32_e32 v73, 0x3f4c422a, v73
	v_mul_f32_e32 v70, 0xc038aa3b, v70
	v_mul_f32_e32 v71, 0xc038aa3b, v71
	v_mul_f32_e32 v72, 0xc038aa3b, v72
	v_mul_f32_e32 v73, 0xc038aa3b, v73
	v_exp_f32_e32 v70, v70
	v_exp_f32_e32 v71, v71
	v_exp_f32_e32 v72, v72
	v_exp_f32_e32 v73, v73
	v_add_f32_e32 v70, 1.0, v70
	v_add_f32_e32 v71, 1.0, v71
	v_add_f32_e32 v72, 1.0, v72
	v_add_f32_e32 v73, 1.0, v73
	v_rcp_f32_e32 v70, v70
	v_rcp_f32_e32 v72, v72
	v_rcp_f32_e32 v73, v73
	v_rcp_f32_e32 v71, v71
	v_pk_mul_f32 v[68:69], v[68:69], v[72:73]
	v_pk_mul_f32 v[66:67], v[66:67], v[70:71]
.LBB0_418:
	s_nop 0
	v_cvt_pk_bf16_f32 v66, v66, v67
	v_cvt_pk_bf16_f32 v67, v68, v69
	v_mov_b32_e32 v248, v66
	v_mov_b32_e32 v249, v67
	s_nop 1
	v_permlane16_swap_b32_e32 v246, v248
	v_permlane16_swap_b32_e32 v247, v249
	v_lshl_add_u64 v[252:253], v[82:83], 0, v[250:251]
	global_store_dwordx4 v[252:253], v[246:249], off offset:256
	s_nop 0
.LBB0_419:
	v_add_u32_e32 v66, 0x80, v154
	v_ashrrev_i32_e32 v67, 31, v66
	v_lshlrev_b64 v[68:69], 6, v[66:67]
	v_lshl_add_u64 v[80:81], s[30:31], 0, v[68:69]
	s_nop 0
	s_and_b64 vcc, exec, s[12:13]
	s_mov_b64 s[14:15], -1
	s_waitcnt vmcnt(14)
	v_pk_add_f32 v[70:71], v[196:197], v[200:201]
	v_pk_add_f32 v[68:69], v[194:195], v[198:199]
	v_pk_add_f32 v[72:73], v[204:205], v[208:209]
	v_pk_add_f32 v[74:75], v[202:203], v[206:207]
	global_load_dwordx4 v[194:197], v[244:245], off offset:3072
	global_load_dwordx4 v[198:201], v[244:245], off offset:3088
	global_load_dwordx4 v[202:205], v[244:245], off offset:3104
	global_load_dwordx4 v[206:209], v[244:245], off offset:3120
	v_pk_add_f32 v[70:71], v[70:71], v[72:73]
	v_pk_add_f32 v[68:69], v[68:69], v[74:75]
	s_nop 0
	v_pk_mov_b32 v[72:73], v[68:69], v[70:71] op_sel:[1,0]
	v_mov_b32_e32 v69, v71
	v_pk_add_f32 v[68:69], v[72:73], v[68:69]
	s_nop 0
	v_add_f32_e32 v68, v68, v69
	v_fmamk_f32 v68, v68, 0x3a800000, v162
	v_rsq_f32_e32 v68, v68
	s_nop 0
	v_pk_mul_f32 v[64:65], v[64:65], v[68:69] op_sel_hi:[1,0]
	v_pk_mul_f32 v[62:63], v[62:63], v[68:69] op_sel_hi:[1,0]
	v_pk_mul_f32 v[60:61], v[60:61], v[68:69] op_sel_hi:[1,0]
	v_pk_mul_f32 v[58:59], v[58:59], v[68:69] op_sel_hi:[1,0]
	v_pk_mul_f32 v[56:57], v[56:57], v[68:69] op_sel_hi:[1,0]
	v_pk_mul_f32 v[54:55], v[54:55], v[68:69] op_sel_hi:[1,0]
	v_pk_mul_f32 v[52:53], v[52:53], v[68:69] op_sel_hi:[1,0]
	v_pk_mul_f32 v[50:51], v[50:51], v[68:69] op_sel_hi:[1,0]
	s_cbranch_vccnz .LBB0_431
	v_mul_f32_e32 v68, v63, v63
	v_mul_f32_e32 v69, v65, v65
	v_fmac_f32_e32 v68, v62, v62
	v_fmac_f32_e32 v69, v64, v64
	v_add_f32_e32 v70, v68, v69
	s_and_b64 vcc, exec, s[10:11]
	v_lshlrev_b64 v[68:69], 9, v[66:67]
	v_mul_f32_e32 v71, v59, v59
	v_mul_f32_e32 v72, v61, v61
	s_cbranch_vccnz .LBB0_426
	v_fma_f32 v73, v58, v58, v71
	v_fma_f32 v75, v60, v60, v72
	v_and_b32_e32 v78, 64, v163
	v_add_f32_e32 v73, v73, v75
	v_xor_b32_e32 v75, 16, v163
	v_add_u32_e32 v80, 64, v78
	v_cmp_lt_i32_e32 vcc, v75, v80
	v_add_f32_e32 v73, v70, v73
	v_lshl_add_u64 v[76:77], v[140:141], 0, v[68:69]
	v_cndmask_b32_e32 v75, v163, v75, vcc
	v_lshlrev_b32_e32 v75, 2, v75
	ds_bpermute_b32 v81, v75, v73
	v_lshlrev_b64 v[78:79], 8, v[66:67]
	global_store_dwordx4 v[76:77], v[62:65], off
	v_cvt_pk_bf16_f32 v74, v62, v63
	v_lshl_add_u64 v[78:79], v[142:143], 0, v[78:79]
	v_cvt_pk_bf16_f32 v75, v64, v65
	global_store_dwordx2 v[78:79], v[74:75], off
	v_xor_b32_e32 v74, 32, v163
	v_cmp_lt_i32_e32 vcc, v74, v80
	s_waitcnt lgkmcnt(0)
	v_add_f32_e32 v73, v73, v81
	global_store_dwordx4 v[76:77], v[58:61], off offset:64
	v_cndmask_b32_e32 v74, v163, v74, vcc
	v_lshlrev_b32_e32 v74, 2, v74
	ds_bpermute_b32 v74, v74, v73
	v_cvt_pk_bf16_f32 v76, v58, v59
	v_cvt_pk_bf16_f32 v77, v60, v61
	global_store_dwordx2 v[78:79], v[76:77], off offset:32
	s_and_saveexec_b64 s[14:15], s[4:5]
	s_cbranch_execz .LBB0_423
	v_lshlrev_b64 v[76:77], 5, v[66:67]
	v_lshl_add_u64 v[76:77], s[42:43], 0, v[76:77]
	s_waitcnt lgkmcnt(0)
	v_add_f32_e32 v73, v73, v74
	global_store_dword v[76:77], v73, off offset:16

.LBB0_434:
	s_and_b64 s[0:1], s[84:85], exec
	s_cselect_b32 s1, s79, s87
	s_cselect_b32 s0, s78, s86
	v_lshlrev_b64 v[66:67], 10, v[66:67]
	v_lshl_add_u64 v[66:67], s[0:1], 0, v[66:67]
	s_lshl_b32 s26, s69, 1
	v_lshl_add_u64 v[66:67], v[66:67], 0, s[26:27]
	s_lshl_b32 s26, s88, 1
	v_lshl_add_u64 v[66:67], v[66:67], 0, s[26:27]
	v_lshlrev_b32_e32 v134, 1, v136
	v_lshl_add_u64 v[66:67], v[66:67], 0, v[134:135]
	s_and_b64 vcc, exec, s[8:9]
	v_cvt_pk_bf16_f32 v62, v62, v63
	v_cvt_pk_bf16_f32 v63, v64, v65
	v_mov_b32_e32 v246, v62
	v_mov_b32_e32 v247, v63
	s_cbranch_vccnz .LBB0_436
	v_mul_f32_e32 v63, 0x3d372713, v59
	v_mov_b32_e32 v64, v59
	v_mul_f32_e32 v63, v59, v63
	v_fmac_f32_e32 v64, v64, v63
	v_mul_f32_e32 v62, 0x3d372713, v58
	v_mul_f32_e32 v63, 0x3f4c422a, v64
	v_mul_f32_e32 v64, 0x3d372713, v60
	v_mul_f32_e32 v65, 0x3d372713, v61
	v_mul_f32_e32 v62, v58, v62
	v_mul_f32_e32 v64, v60, v64
	v_mul_f32_e32 v65, v61, v65
	v_fma_f32 v62, v58, v62, v58
	v_fma_f32 v64, v60, v64, v60
	v_fma_f32 v65, v61, v65, v61
	v_mul_f32_e32 v62, 0x3f4c422a, v62
	v_mul_f32_e32 v64, 0x3f4c422a, v64
	v_mul_f32_e32 v65, 0x3f4c422a, v65
	v_mul_f32_e32 v62, 0xc038aa3b, v62
	v_mul_f32_e32 v63, 0xc038aa3b, v63
	v_mul_f32_e32 v64, 0xc038aa3b, v64
	v_mul_f32_e32 v65, 0xc038aa3b, v65
	v_exp_f32_e32 v62, v62
	v_exp_f32_e32 v63, v63
	v_exp_f32_e32 v64, v64
	v_exp_f32_e32 v65, v65
	v_add_f32_e32 v62, 1.0, v62
	v_add_f32_e32 v63, 1.0, v63
	v_add_f32_e32 v64, 1.0, v64
	v_add_f32_e32 v65, 1.0, v65
	v_rcp_f32_e32 v62, v62
	v_rcp_f32_e32 v64, v64
	v_rcp_f32_e32 v65, v65
	v_rcp_f32_e32 v63, v63
	v_pk_mul_f32 v[60:61], v[60:61], v[64:65]
	v_pk_mul_f32 v[58:59], v[58:59], v[62:63]
.LBB0_436:
	s_and_b64 vcc, exec, s[8:9]
	v_cvt_pk_bf16_f32 v58, v58, v59
	v_cvt_pk_bf16_f32 v59, v60, v61
	v_mov_b32_e32 v248, v58
	v_mov_b32_e32 v249, v59
	s_nop 1
	v_permlane16_swap_b32_e32 v246, v248
	v_permlane16_swap_b32_e32 v247, v249
	v_lshl_add_u64 v[252:253], v[66:67], 0, v[250:251]
	global_store_dwordx4 v[252:253], v[246:249], off
	s_nop 0
	s_cbranch_vccnz .LBB0_438
	v_mul_f32_e32 v59, 0x3d372713, v55
	v_mov_b32_e32 v60, v55
	v_mul_f32_e32 v59, v55, v59
	v_fmac_f32_e32 v60, v60, v59
	v_mul_f32_e32 v58, 0x3d372713, v54
	v_mul_f32_e32 v59, 0x3f4c422a, v60
	v_mul_f32_e32 v60, 0x3d372713, v56
	v_mul_f32_e32 v61, 0x3d372713, v57
	v_mul_f32_e32 v58, v54, v58
	v_mul_f32_e32 v60, v56, v60
	v_mul_f32_e32 v61, v57, v61
	v_fma_f32 v58, v54, v58, v54
	v_fma_f32 v60, v56, v60, v56
	v_fma_f32 v61, v57, v61, v57
	v_mul_f32_e32 v58, 0x3f4c422a, v58
	v_mul_f32_e32 v60, 0x3f4c422a, v60
	v_mul_f32_e32 v61, 0x3f4c422a, v61
	v_mul_f32_e32 v58, 0xc038aa3b, v58
	v_mul_f32_e32 v59, 0xc038aa3b, v59
	v_mul_f32_e32 v60, 0xc038aa3b, v60
	v_mul_f32_e32 v61, 0xc038aa3b, v61
	v_exp_f32_e32 v58, v58
	v_exp_f32_e32 v59, v59
	v_exp_f32_e32 v60, v60
	v_exp_f32_e32 v61, v61
	v_add_f32_e32 v58, 1.0, v58
	v_add_f32_e32 v59, 1.0, v59
	v_add_f32_e32 v60, 1.0, v60
	v_add_f32_e32 v61, 1.0, v61
	v_rcp_f32_e32 v58, v58
	v_rcp_f32_e32 v60, v60
	v_rcp_f32_e32 v61, v61
	v_rcp_f32_e32 v59, v59
	v_pk_mul_f32 v[56:57], v[56:57], v[60:61]
	v_pk_mul_f32 v[54:55], v[54:55], v[58:59]
.LBB0_438:
	s_and_b64 vcc, exec, s[8:9]
	v_cvt_pk_bf16_f32 v54, v54, v55
	v_cvt_pk_bf16_f32 v55, v56, v57
	v_mov_b32_e32 v246, v54
	v_mov_b32_e32 v247, v55
	s_cbranch_vccnz .LBB0_440
	v_mul_f32_e32 v55, 0x3d372713, v51
	v_mov_b32_e32 v56, v51
	v_mul_f32_e32 v55, v51, v55
	v_fmac_f32_e32 v56, v56, v55
	v_mul_f32_e32 v54, 0x3d372713, v50
	v_mul_f32_e32 v55, 0x3f4c422a, v56
	v_mul_f32_e32 v56, 0x3d372713, v52
	v_mul_f32_e32 v57, 0x3d372713, v53
	v_mul_f32_e32 v54, v50, v54
	v_mul_f32_e32 v56, v52, v56
	v_mul_f32_e32 v57, v53, v57
	v_fma_f32 v54, v50, v54, v50
	v_fma_f32 v56, v52, v56, v52
	v_fma_f32 v57, v53, v57, v53
	v_mul_f32_e32 v54, 0x3f4c422a, v54
	v_mul_f32_e32 v56, 0x3f4c422a, v56
	v_mul_f32_e32 v57, 0x3f4c422a, v57
	v_mul_f32_e32 v54, 0xc038aa3b, v54
	v_mul_f32_e32 v55, 0xc038aa3b, v55
	v_mul_f32_e32 v56, 0xc038aa3b, v56
	v_mul_f32_e32 v57, 0xc038aa3b, v57
	v_exp_f32_e32 v54, v54
	v_exp_f32_e32 v55, v55
	v_exp_f32_e32 v56, v56
	v_exp_f32_e32 v57, v57
	v_add_f32_e32 v54, 1.0, v54
	v_add_f32_e32 v55, 1.0, v55
	v_add_f32_e32 v56, 1.0, v56
	v_add_f32_e32 v57, 1.0, v57
	v_rcp_f32_e32 v54, v54
	v_rcp_f32_e32 v56, v56
	v_rcp_f32_e32 v57, v57
	v_rcp_f32_e32 v55, v55
	v_pk_mul_f32 v[52:53], v[52:53], v[56:57]
	v_pk_mul_f32 v[50:51], v[50:51], v[54:55]
.LBB0_440:
	s_nop 0
	v_cvt_pk_bf16_f32 v50, v50, v51
	v_cvt_pk_bf16_f32 v51, v52, v53
	v_mov_b32_e32 v248, v50
	v_mov_b32_e32 v249, v51
	s_nop 1
	v_permlane16_swap_b32_e32 v246, v248
	v_permlane16_swap_b32_e32 v247, v249
	v_lshl_add_u64 v[252:253], v[66:67], 0, v[250:251]
	global_store_dwordx4 v[252:253], v[246:249], off offset:256
	s_nop 0
.LBB0_441:
	v_add_u32_e32 v50, 0x90, v154
	v_ashrrev_i32_e32 v51, 31, v50
	v_lshlrev_b64 v[52:53], 6, v[50:51]
	v_lshl_add_u64 v[64:65], s[30:31], 0, v[52:53]
	s_nop 0
	s_and_b64 vcc, exec, s[12:13]
	s_mov_b64 s[14:15], -1
	s_waitcnt vmcnt(14)
	v_pk_add_f32 v[54:55], v[212:213], v[216:217]
	v_pk_add_f32 v[52:53], v[210:211], v[214:215]
	v_pk_add_f32 v[56:57], v[220:221], v[224:225]
	v_pk_add_f32 v[58:59], v[218:219], v[222:223]
	v_pk_add_f32 v[54:55], v[54:55], v[56:57]
	v_pk_add_f32 v[52:53], v[52:53], v[58:59]
	s_nop 0
	v_pk_mov_b32 v[56:57], v[52:53], v[54:55] op_sel:[1,0]
	v_mov_b32_e32 v53, v55
	v_pk_add_f32 v[52:53], v[56:57], v[52:53]
	s_nop 0
	v_add_f32_e32 v52, v52, v53
	v_fmamk_f32 v52, v52, 0x3a800000, v162
	v_rsq_f32_e32 v52, v52
	s_nop 0
	v_pk_mul_f32 v[48:49], v[48:49], v[52:53] op_sel_hi:[1,0]
	v_pk_mul_f32 v[46:47], v[46:47], v[52:53] op_sel_hi:[1,0]
	v_pk_mul_f32 v[44:45], v[44:45], v[52:53] op_sel_hi:[1,0]
	v_pk_mul_f32 v[42:43], v[42:43], v[52:53] op_sel_hi:[1,0]
	v_pk_mul_f32 v[40:41], v[40:41], v[52:53] op_sel_hi:[1,0]
	v_pk_mul_f32 v[38:39], v[38:39], v[52:53] op_sel_hi:[1,0]
	v_pk_mul_f32 v[36:37], v[36:37], v[52:53] op_sel_hi:[1,0]
	v_pk_mul_f32 v[34:35], v[34:35], v[52:53] op_sel_hi:[1,0]
	s_cbranch_vccnz .LBB0_453
	v_mul_f32_e32 v52, v47, v47
	v_mul_f32_e32 v53, v49, v49
	v_fmac_f32_e32 v52, v46, v46
	v_fmac_f32_e32 v53, v48, v48
	v_add_f32_e32 v54, v52, v53
	s_and_b64 vcc, exec, s[10:11]
	v_lshlrev_b64 v[52:53], 9, v[50:51]
	v_mul_f32_e32 v55, v43, v43
	v_mul_f32_e32 v56, v45, v45
	s_cbranch_vccnz .LBB0_448
	v_fma_f32 v57, v42, v42, v55
	v_fma_f32 v59, v44, v44, v56
	v_and_b32_e32 v62, 64, v163
	v_add_f32_e32 v57, v57, v59
	v_xor_b32_e32 v59, 16, v163
	v_add_u32_e32 v64, 64, v62
	v_cmp_lt_i32_e32 vcc, v59, v64
	v_add_f32_e32 v57, v54, v57
	v_lshl_add_u64 v[60:61], v[140:141], 0, v[52:53]
	v_cndmask_b32_e32 v59, v163, v59, vcc
	v_lshlrev_b32_e32 v59, 2, v59
	ds_bpermute_b32 v65, v59, v57
	v_lshlrev_b64 v[62:63], 8, v[50:51]
	global_store_dwordx4 v[60:61], v[46:49], off
	v_cvt_pk_bf16_f32 v58, v46, v47
	v_lshl_add_u64 v[62:63], v[142:143], 0, v[62:63]
	v_cvt_pk_bf16_f32 v59, v48, v49
	global_store_dwordx2 v[62:63], v[58:59], off
	v_xor_b32_e32 v58, 32, v163
	v_cmp_lt_i32_e32 vcc, v58, v64
	s_waitcnt lgkmcnt(0)
	v_add_f32_e32 v57, v57, v65
	global_store_dwordx4 v[60:61], v[42:45], off offset:64
	v_cndmask_b32_e32 v58, v163, v58, vcc
	v_lshlrev_b32_e32 v58, 2, v58
	ds_bpermute_b32 v58, v58, v57
	v_cvt_pk_bf16_f32 v60, v42, v43
	v_cvt_pk_bf16_f32 v61, v44, v45
	global_store_dwordx2 v[62:63], v[60:61], off offset:32
	s_and_saveexec_b64 s[14:15], s[4:5]
	s_cbranch_execz .LBB0_445
	v_lshlrev_b64 v[60:61], 5, v[50:51]
	v_lshl_add_u64 v[60:61], s[42:43], 0, v[60:61]
	s_waitcnt lgkmcnt(0)
	v_add_f32_e32 v57, v57, v58
	global_store_dword v[60:61], v57, off offset:16

.LBB0_456:
	s_and_b64 s[0:1], s[84:85], exec
	s_cselect_b32 s1, s79, s87
	s_cselect_b32 s0, s78, s86
	v_lshlrev_b64 v[50:51], 10, v[50:51]
	v_lshl_add_u64 v[50:51], s[0:1], 0, v[50:51]
	s_lshl_b32 s26, s69, 1
	v_lshl_add_u64 v[50:51], v[50:51], 0, s[26:27]
	s_lshl_b32 s26, s88, 1
	v_lshl_add_u64 v[50:51], v[50:51], 0, s[26:27]
	v_lshlrev_b32_e32 v134, 1, v136
	v_lshl_add_u64 v[50:51], v[50:51], 0, v[134:135]
	s_and_b64 vcc, exec, s[8:9]
	v_cvt_pk_bf16_f32 v46, v46, v47
	v_cvt_pk_bf16_f32 v47, v48, v49
	v_mov_b32_e32 v246, v46
	v_mov_b32_e32 v247, v47
	s_cbranch_vccnz .LBB0_458
	v_mul_f32_e32 v47, 0x3d372713, v43
	v_mov_b32_e32 v48, v43
	v_mul_f32_e32 v47, v43, v47
	v_fmac_f32_e32 v48, v48, v47
	v_mul_f32_e32 v46, 0x3d372713, v42
	v_mul_f32_e32 v47, 0x3f4c422a, v48
	v_mul_f32_e32 v48, 0x3d372713, v44
	v_mul_f32_e32 v49, 0x3d372713, v45
	v_mul_f32_e32 v46, v42, v46
	v_mul_f32_e32 v48, v44, v48
	v_mul_f32_e32 v49, v45, v49
	v_fma_f32 v46, v42, v46, v42
	v_fma_f32 v48, v44, v48, v44
	v_fma_f32 v49, v45, v49, v45
	v_mul_f32_e32 v46, 0x3f4c422a, v46
	v_mul_f32_e32 v48, 0x3f4c422a, v48
	v_mul_f32_e32 v49, 0x3f4c422a, v49
	v_mul_f32_e32 v46, 0xc038aa3b, v46
	v_mul_f32_e32 v47, 0xc038aa3b, v47
	v_mul_f32_e32 v48, 0xc038aa3b, v48
	v_mul_f32_e32 v49, 0xc038aa3b, v49
	v_exp_f32_e32 v46, v46
	v_exp_f32_e32 v47, v47
	v_exp_f32_e32 v48, v48
	v_exp_f32_e32 v49, v49
	v_add_f32_e32 v46, 1.0, v46
	v_add_f32_e32 v47, 1.0, v47
	v_add_f32_e32 v48, 1.0, v48
	v_add_f32_e32 v49, 1.0, v49
	v_rcp_f32_e32 v46, v46
	v_rcp_f32_e32 v48, v48
	v_rcp_f32_e32 v49, v49
	v_rcp_f32_e32 v47, v47
	v_pk_mul_f32 v[44:45], v[44:45], v[48:49]
	v_pk_mul_f32 v[42:43], v[42:43], v[46:47]
.LBB0_458:
	s_and_b64 vcc, exec, s[8:9]
	v_cvt_pk_bf16_f32 v42, v42, v43
	v_cvt_pk_bf16_f32 v43, v44, v45
	v_mov_b32_e32 v248, v42
	v_mov_b32_e32 v249, v43
	s_nop 1
	v_permlane16_swap_b32_e32 v246, v248
	v_permlane16_swap_b32_e32 v247, v249
	v_lshl_add_u64 v[252:253], v[50:51], 0, v[250:251]
	global_store_dwordx4 v[252:253], v[246:249], off
	s_nop 0
	s_cbranch_vccnz .LBB0_460
	v_mul_f32_e32 v43, 0x3d372713, v39
	v_mov_b32_e32 v44, v39
	v_mul_f32_e32 v43, v39, v43
	v_fmac_f32_e32 v44, v44, v43
	v_mul_f32_e32 v42, 0x3d372713, v38
	v_mul_f32_e32 v43, 0x3f4c422a, v44
	v_mul_f32_e32 v44, 0x3d372713, v40
	v_mul_f32_e32 v45, 0x3d372713, v41
	v_mul_f32_e32 v42, v38, v42
	v_mul_f32_e32 v44, v40, v44
	v_mul_f32_e32 v45, v41, v45
	v_fma_f32 v42, v38, v42, v38
	v_fma_f32 v44, v40, v44, v40
	v_fma_f32 v45, v41, v45, v41
	v_mul_f32_e32 v42, 0x3f4c422a, v42
	v_mul_f32_e32 v44, 0x3f4c422a, v44
	v_mul_f32_e32 v45, 0x3f4c422a, v45
	v_mul_f32_e32 v42, 0xc038aa3b, v42
	v_mul_f32_e32 v43, 0xc038aa3b, v43
	v_mul_f32_e32 v44, 0xc038aa3b, v44
	v_mul_f32_e32 v45, 0xc038aa3b, v45
	v_exp_f32_e32 v42, v42
	v_exp_f32_e32 v43, v43
	v_exp_f32_e32 v44, v44
	v_exp_f32_e32 v45, v45
	v_add_f32_e32 v42, 1.0, v42
	v_add_f32_e32 v43, 1.0, v43
	v_add_f32_e32 v44, 1.0, v44
	v_add_f32_e32 v45, 1.0, v45
	v_rcp_f32_e32 v42, v42
	v_rcp_f32_e32 v44, v44
	v_rcp_f32_e32 v45, v45
	v_rcp_f32_e32 v43, v43
	v_pk_mul_f32 v[40:41], v[40:41], v[44:45]
	v_pk_mul_f32 v[38:39], v[38:39], v[42:43]
.LBB0_460:
	s_and_b64 vcc, exec, s[8:9]
	v_cvt_pk_bf16_f32 v38, v38, v39
	v_cvt_pk_bf16_f32 v39, v40, v41
	v_mov_b32_e32 v246, v38
	v_mov_b32_e32 v247, v39
	s_cbranch_vccnz .LBB0_462
	v_mul_f32_e32 v39, 0x3d372713, v35
	v_mov_b32_e32 v40, v35
	v_mul_f32_e32 v39, v35, v39
	v_fmac_f32_e32 v40, v40, v39
	v_mul_f32_e32 v38, 0x3d372713, v34
	v_mul_f32_e32 v39, 0x3f4c422a, v40
	v_mul_f32_e32 v40, 0x3d372713, v36
	v_mul_f32_e32 v41, 0x3d372713, v37
	v_mul_f32_e32 v38, v34, v38
	v_mul_f32_e32 v40, v36, v40
	v_mul_f32_e32 v41, v37, v41
	v_fma_f32 v38, v34, v38, v34
	v_fma_f32 v40, v36, v40, v36
	v_fma_f32 v41, v37, v41, v37
	v_mul_f32_e32 v38, 0x3f4c422a, v38
	v_mul_f32_e32 v40, 0x3f4c422a, v40
	v_mul_f32_e32 v41, 0x3f4c422a, v41
	v_mul_f32_e32 v38, 0xc038aa3b, v38
	v_mul_f32_e32 v39, 0xc038aa3b, v39
	v_mul_f32_e32 v40, 0xc038aa3b, v40
	v_mul_f32_e32 v41, 0xc038aa3b, v41
	v_exp_f32_e32 v38, v38
	v_exp_f32_e32 v39, v39
	v_exp_f32_e32 v40, v40
	v_exp_f32_e32 v41, v41
	v_add_f32_e32 v38, 1.0, v38
	v_add_f32_e32 v39, 1.0, v39
	v_add_f32_e32 v40, 1.0, v40
	v_add_f32_e32 v41, 1.0, v41
	v_rcp_f32_e32 v38, v38
	v_rcp_f32_e32 v40, v40
	v_rcp_f32_e32 v41, v41
	v_rcp_f32_e32 v39, v39
	v_pk_mul_f32 v[36:37], v[36:37], v[40:41]
	v_pk_mul_f32 v[34:35], v[34:35], v[38:39]
.LBB0_462:
	s_nop 0
	v_cvt_pk_bf16_f32 v34, v34, v35
	v_cvt_pk_bf16_f32 v35, v36, v37
	v_mov_b32_e32 v248, v34
	v_mov_b32_e32 v249, v35
	s_nop 1
	v_permlane16_swap_b32_e32 v246, v248
	v_permlane16_swap_b32_e32 v247, v249
	v_lshl_add_u64 v[252:253], v[50:51], 0, v[250:251]
	global_store_dwordx4 v[252:253], v[246:249], off offset:256
	s_nop 0
.LBB0_463:
	v_add_u32_e32 v34, 0xa0, v154
	v_ashrrev_i32_e32 v35, 31, v34
	v_lshlrev_b64 v[36:37], 6, v[34:35]
	v_lshl_add_u64 v[48:49], s[30:31], 0, v[36:37]
	s_nop 0
	s_and_b64 vcc, exec, s[12:13]
	s_mov_b64 s[14:15], -1
	s_waitcnt vmcnt(10)
	v_pk_add_f32 v[38:39], v[228:229], v[232:233]
	v_pk_add_f32 v[36:37], v[226:227], v[230:231]
	v_pk_add_f32 v[40:41], v[236:237], v[240:241]
	v_pk_add_f32 v[42:43], v[234:235], v[238:239]
	v_pk_add_f32 v[38:39], v[38:39], v[40:41]
	v_pk_add_f32 v[36:37], v[36:37], v[42:43]
	s_nop 0
	v_pk_mov_b32 v[40:41], v[36:37], v[38:39] op_sel:[1,0]
	v_mov_b32_e32 v37, v39
	v_pk_add_f32 v[36:37], v[40:41], v[36:37]
	s_nop 0
	v_add_f32_e32 v36, v36, v37
	v_fmamk_f32 v36, v36, 0x3a800000, v162
	v_rsq_f32_e32 v36, v36
	s_nop 0
	v_pk_mul_f32 v[32:33], v[32:33], v[36:37] op_sel_hi:[1,0]
	v_pk_mul_f32 v[30:31], v[30:31], v[36:37] op_sel_hi:[1,0]
	v_pk_mul_f32 v[28:29], v[28:29], v[36:37] op_sel_hi:[1,0]
	v_pk_mul_f32 v[26:27], v[26:27], v[36:37] op_sel_hi:[1,0]
	v_pk_mul_f32 v[24:25], v[24:25], v[36:37] op_sel_hi:[1,0]
	v_pk_mul_f32 v[22:23], v[22:23], v[36:37] op_sel_hi:[1,0]
	v_pk_mul_f32 v[20:21], v[20:21], v[36:37] op_sel_hi:[1,0]
	v_pk_mul_f32 v[18:19], v[18:19], v[36:37] op_sel_hi:[1,0]
	s_cbranch_vccnz .LBB0_475
	v_mul_f32_e32 v36, v31, v31
	v_mul_f32_e32 v37, v33, v33
	v_fmac_f32_e32 v36, v30, v30
	v_fmac_f32_e32 v37, v32, v32
	v_add_f32_e32 v38, v36, v37
	s_and_b64 vcc, exec, s[10:11]
	v_lshlrev_b64 v[36:37], 9, v[34:35]
	v_mul_f32_e32 v39, v27, v27
	v_mul_f32_e32 v40, v29, v29
	s_cbranch_vccnz .LBB0_470
	v_fma_f32 v41, v26, v26, v39
	v_fma_f32 v43, v28, v28, v40
	v_and_b32_e32 v46, 64, v163
	v_add_f32_e32 v41, v41, v43
	v_xor_b32_e32 v43, 16, v163
	v_add_u32_e32 v48, 64, v46
	v_cmp_lt_i32_e32 vcc, v43, v48
	v_add_f32_e32 v41, v38, v41
	v_lshl_add_u64 v[44:45], v[140:141], 0, v[36:37]
	v_cndmask_b32_e32 v43, v163, v43, vcc
	v_lshlrev_b32_e32 v43, 2, v43
	ds_bpermute_b32 v49, v43, v41
	v_lshlrev_b64 v[46:47], 8, v[34:35]
	global_store_dwordx4 v[44:45], v[30:33], off
	v_cvt_pk_bf16_f32 v42, v30, v31
	v_lshl_add_u64 v[46:47], v[142:143], 0, v[46:47]
	v_cvt_pk_bf16_f32 v43, v32, v33
	global_store_dwordx2 v[46:47], v[42:43], off
	v_xor_b32_e32 v42, 32, v163
	v_cmp_lt_i32_e32 vcc, v42, v48
	s_waitcnt lgkmcnt(0)
	v_add_f32_e32 v41, v41, v49
	global_store_dwordx4 v[44:45], v[26:29], off offset:64
	v_cndmask_b32_e32 v42, v163, v42, vcc
	v_lshlrev_b32_e32 v42, 2, v42
	ds_bpermute_b32 v42, v42, v41
	v_cvt_pk_bf16_f32 v44, v26, v27
	v_cvt_pk_bf16_f32 v45, v28, v29
	global_store_dwordx2 v[46:47], v[44:45], off offset:32
	s_and_saveexec_b64 s[14:15], s[4:5]
	s_cbranch_execz .LBB0_467
	v_lshlrev_b64 v[44:45], 5, v[34:35]
	v_lshl_add_u64 v[44:45], s[42:43], 0, v[44:45]
	s_waitcnt lgkmcnt(0)
	v_add_f32_e32 v41, v41, v42
	global_store_dword v[44:45], v41, off offset:16

.LBB0_478:
	s_and_b64 s[0:1], s[84:85], exec
	s_cselect_b32 s1, s79, s87
	s_cselect_b32 s0, s78, s86
	v_lshlrev_b64 v[34:35], 10, v[34:35]
	v_lshl_add_u64 v[34:35], s[0:1], 0, v[34:35]
	s_lshl_b32 s26, s69, 1
	v_lshl_add_u64 v[34:35], v[34:35], 0, s[26:27]
	s_lshl_b32 s26, s88, 1
	v_lshl_add_u64 v[34:35], v[34:35], 0, s[26:27]
	v_lshlrev_b32_e32 v134, 1, v136
	v_lshl_add_u64 v[34:35], v[34:35], 0, v[134:135]
	s_and_b64 vcc, exec, s[8:9]
	v_cvt_pk_bf16_f32 v30, v30, v31
	v_cvt_pk_bf16_f32 v31, v32, v33
	v_mov_b32_e32 v246, v30
	v_mov_b32_e32 v247, v31
	s_cbranch_vccnz .LBB0_480
	v_mul_f32_e32 v31, 0x3d372713, v27
	v_mov_b32_e32 v32, v27
	v_mul_f32_e32 v31, v27, v31
	v_fmac_f32_e32 v32, v32, v31
	v_mul_f32_e32 v30, 0x3d372713, v26
	v_mul_f32_e32 v31, 0x3f4c422a, v32
	v_mul_f32_e32 v32, 0x3d372713, v28
	v_mul_f32_e32 v33, 0x3d372713, v29
	v_mul_f32_e32 v30, v26, v30
	v_mul_f32_e32 v32, v28, v32
	v_mul_f32_e32 v33, v29, v33
	v_fma_f32 v30, v26, v30, v26
	v_fma_f32 v32, v28, v32, v28
	v_fma_f32 v33, v29, v33, v29
	v_mul_f32_e32 v30, 0x3f4c422a, v30
	v_mul_f32_e32 v32, 0x3f4c422a, v32
	v_mul_f32_e32 v33, 0x3f4c422a, v33
	v_mul_f32_e32 v30, 0xc038aa3b, v30
	v_mul_f32_e32 v31, 0xc038aa3b, v31
	v_mul_f32_e32 v32, 0xc038aa3b, v32
	v_mul_f32_e32 v33, 0xc038aa3b, v33
	v_exp_f32_e32 v30, v30
	v_exp_f32_e32 v31, v31
	v_exp_f32_e32 v32, v32
	v_exp_f32_e32 v33, v33
	v_add_f32_e32 v30, 1.0, v30
	v_add_f32_e32 v31, 1.0, v31
	v_add_f32_e32 v32, 1.0, v32
	v_add_f32_e32 v33, 1.0, v33
	v_rcp_f32_e32 v30, v30
	v_rcp_f32_e32 v32, v32
	v_rcp_f32_e32 v33, v33
	v_rcp_f32_e32 v31, v31
	v_pk_mul_f32 v[28:29], v[28:29], v[32:33]
	v_pk_mul_f32 v[26:27], v[26:27], v[30:31]
.LBB0_480:
	s_and_b64 vcc, exec, s[8:9]
	v_cvt_pk_bf16_f32 v26, v26, v27
	v_cvt_pk_bf16_f32 v27, v28, v29
	v_mov_b32_e32 v248, v26
	v_mov_b32_e32 v249, v27
	s_nop 1
	v_permlane16_swap_b32_e32 v246, v248
	v_permlane16_swap_b32_e32 v247, v249
	v_lshl_add_u64 v[252:253], v[34:35], 0, v[250:251]
	global_store_dwordx4 v[252:253], v[246:249], off
	s_nop 0
	s_cbranch_vccnz .LBB0_482
	v_mul_f32_e32 v27, 0x3d372713, v23
	v_mov_b32_e32 v28, v23
	v_mul_f32_e32 v27, v23, v27
	v_fmac_f32_e32 v28, v28, v27
	v_mul_f32_e32 v26, 0x3d372713, v22
	v_mul_f32_e32 v27, 0x3f4c422a, v28
	v_mul_f32_e32 v28, 0x3d372713, v24
	v_mul_f32_e32 v29, 0x3d372713, v25
	v_mul_f32_e32 v26, v22, v26
	v_mul_f32_e32 v28, v24, v28
	v_mul_f32_e32 v29, v25, v29
	v_fma_f32 v26, v22, v26, v22
	v_fma_f32 v28, v24, v28, v24
	v_fma_f32 v29, v25, v29, v25
	v_mul_f32_e32 v26, 0x3f4c422a, v26
	v_mul_f32_e32 v28, 0x3f4c422a, v28
	v_mul_f32_e32 v29, 0x3f4c422a, v29
	v_mul_f32_e32 v26, 0xc038aa3b, v26
	v_mul_f32_e32 v27, 0xc038aa3b, v27
	v_mul_f32_e32 v28, 0xc038aa3b, v28
	v_mul_f32_e32 v29, 0xc038aa3b, v29
	v_exp_f32_e32 v26, v26
	v_exp_f32_e32 v27, v27
	v_exp_f32_e32 v28, v28
	v_exp_f32_e32 v29, v29
	v_add_f32_e32 v26, 1.0, v26
	v_add_f32_e32 v27, 1.0, v27
	v_add_f32_e32 v28, 1.0, v28
	v_add_f32_e32 v29, 1.0, v29
	v_rcp_f32_e32 v26, v26
	v_rcp_f32_e32 v28, v28
	v_rcp_f32_e32 v29, v29
	v_rcp_f32_e32 v27, v27
	v_pk_mul_f32 v[24:25], v[24:25], v[28:29]
	v_pk_mul_f32 v[22:23], v[22:23], v[26:27]
.LBB0_482:
	s_and_b64 vcc, exec, s[8:9]
	v_cvt_pk_bf16_f32 v22, v22, v23
	v_cvt_pk_bf16_f32 v23, v24, v25
	v_mov_b32_e32 v246, v22
	v_mov_b32_e32 v247, v23
	s_cbranch_vccnz .LBB0_484
	v_mul_f32_e32 v23, 0x3d372713, v19
	v_mov_b32_e32 v24, v19
	v_mul_f32_e32 v23, v19, v23
	v_fmac_f32_e32 v24, v24, v23
	v_mul_f32_e32 v22, 0x3d372713, v18
	v_mul_f32_e32 v23, 0x3f4c422a, v24
	v_mul_f32_e32 v24, 0x3d372713, v20
	v_mul_f32_e32 v25, 0x3d372713, v21
	v_mul_f32_e32 v22, v18, v22
	v_mul_f32_e32 v24, v20, v24
	v_mul_f32_e32 v25, v21, v25
	v_fma_f32 v22, v18, v22, v18
	v_fma_f32 v24, v20, v24, v20
	v_fma_f32 v25, v21, v25, v21
	v_mul_f32_e32 v22, 0x3f4c422a, v22
	v_mul_f32_e32 v24, 0x3f4c422a, v24
	v_mul_f32_e32 v25, 0x3f4c422a, v25
	v_mul_f32_e32 v22, 0xc038aa3b, v22
	v_mul_f32_e32 v23, 0xc038aa3b, v23
	v_mul_f32_e32 v24, 0xc038aa3b, v24
	v_mul_f32_e32 v25, 0xc038aa3b, v25
	v_exp_f32_e32 v22, v22
	v_exp_f32_e32 v23, v23
	v_exp_f32_e32 v24, v24
	v_exp_f32_e32 v25, v25
	v_add_f32_e32 v22, 1.0, v22
	v_add_f32_e32 v23, 1.0, v23
	v_add_f32_e32 v24, 1.0, v24
	v_add_f32_e32 v25, 1.0, v25
	v_rcp_f32_e32 v22, v22
	v_rcp_f32_e32 v24, v24
	v_rcp_f32_e32 v25, v25
	v_rcp_f32_e32 v23, v23
	v_pk_mul_f32 v[20:21], v[20:21], v[24:25]
	v_pk_mul_f32 v[18:19], v[18:19], v[22:23]
.LBB0_484:
	s_nop 0
	v_cvt_pk_bf16_f32 v18, v18, v19
	v_cvt_pk_bf16_f32 v19, v20, v21
	v_mov_b32_e32 v248, v18
	v_mov_b32_e32 v249, v19
	s_nop 1
	v_permlane16_swap_b32_e32 v246, v248
	v_permlane16_swap_b32_e32 v247, v249
	v_lshl_add_u64 v[252:253], v[34:35], 0, v[250:251]
	global_store_dwordx4 v[252:253], v[246:249], off offset:256
	s_nop 0
.LBB0_485:
	v_add_u32_e32 v18, 0xb0, v154
	v_ashrrev_i32_e32 v19, 31, v18
	v_lshlrev_b64 v[20:21], 6, v[18:19]
	v_lshl_add_u64 v[32:33], s[30:31], 0, v[20:21]
	s_nop 0
	s_and_b64 vcc, exec, s[12:13]
	s_mov_b64 s[12:13], -1
	s_waitcnt vmcnt(6)
	v_pk_add_f32 v[22:23], v[196:197], v[200:201]
	v_pk_add_f32 v[20:21], v[194:195], v[198:199]
	v_pk_add_f32 v[24:25], v[204:205], v[208:209]
	v_pk_add_f32 v[26:27], v[202:203], v[206:207]
	v_pk_add_f32 v[22:23], v[22:23], v[24:25]
	v_pk_add_f32 v[20:21], v[20:21], v[26:27]
	s_nop 0
	v_pk_mov_b32 v[24:25], v[20:21], v[22:23] op_sel:[1,0]
	v_mov_b32_e32 v21, v23
	v_pk_add_f32 v[20:21], v[24:25], v[20:21]
	s_nop 0
	v_add_f32_e32 v20, v20, v21
	v_fmamk_f32 v20, v20, 0x3a800000, v162
	v_rsq_f32_e32 v20, v20
	s_nop 0
	v_pk_mul_f32 v[16:17], v[16:17], v[20:21] op_sel_hi:[1,0]
	v_pk_mul_f32 v[14:15], v[14:15], v[20:21] op_sel_hi:[1,0]
	v_pk_mul_f32 v[12:13], v[12:13], v[20:21] op_sel_hi:[1,0]
	v_pk_mul_f32 v[10:11], v[10:11], v[20:21] op_sel_hi:[1,0]
	v_pk_mul_f32 v[8:9], v[8:9], v[20:21] op_sel_hi:[1,0]
	v_pk_mul_f32 v[6:7], v[6:7], v[20:21] op_sel_hi:[1,0]
	v_pk_mul_f32 v[4:5], v[4:5], v[20:21] op_sel_hi:[1,0]
	v_pk_mul_f32 v[2:3], v[2:3], v[20:21] op_sel_hi:[1,0]
	s_cbranch_vccnz .LBB0_498
	v_mul_f32_e32 v20, v15, v15
	v_mul_f32_e32 v21, v17, v17
	v_fmac_f32_e32 v20, v14, v14
	v_fmac_f32_e32 v21, v16, v16
	v_add_f32_e32 v22, v20, v21
	s_and_b64 vcc, exec, s[10:11]
	v_lshlrev_b64 v[20:21], 9, v[18:19]
	v_mul_f32_e32 v23, v11, v11
	v_mul_f32_e32 v24, v13, v13
	s_cbranch_vccnz .LBB0_492
	v_fma_f32 v25, v10, v10, v23
	v_fma_f32 v27, v12, v12, v24
	v_and_b32_e32 v30, 64, v163
	v_add_f32_e32 v25, v25, v27
	v_xor_b32_e32 v27, 16, v163
	v_add_u32_e32 v32, 64, v30
	v_cmp_lt_i32_e32 vcc, v27, v32
	v_add_f32_e32 v25, v22, v25
	v_lshl_add_u64 v[28:29], v[140:141], 0, v[20:21]
	v_cndmask_b32_e32 v27, v163, v27, vcc
	v_lshlrev_b32_e32 v27, 2, v27
	ds_bpermute_b32 v33, v27, v25
	v_lshlrev_b64 v[30:31], 8, v[18:19]
	global_store_dwordx4 v[28:29], v[14:17], off
	v_cvt_pk_bf16_f32 v26, v14, v15
	v_lshl_add_u64 v[30:31], v[142:143], 0, v[30:31]
	v_cvt_pk_bf16_f32 v27, v16, v17
	global_store_dwordx2 v[30:31], v[26:27], off
	v_xor_b32_e32 v26, 32, v163
	v_cmp_lt_i32_e32 vcc, v26, v32
	s_waitcnt lgkmcnt(0)
	v_add_f32_e32 v25, v25, v33
	global_store_dwordx4 v[28:29], v[10:13], off offset:64
	v_cndmask_b32_e32 v26, v163, v26, vcc
	v_lshlrev_b32_e32 v26, 2, v26
	ds_bpermute_b32 v26, v26, v25
	v_cvt_pk_bf16_f32 v28, v10, v11
	v_cvt_pk_bf16_f32 v29, v12, v13
	global_store_dwordx2 v[30:31], v[28:29], off offset:32
	s_and_saveexec_b64 s[10:11], s[4:5]
	s_cbranch_execz .LBB0_489
	v_lshlrev_b64 v[28:29], 5, v[18:19]
	v_lshl_add_u64 v[28:29], s[42:43], 0, v[28:29]
	s_waitcnt lgkmcnt(0)
	v_add_f32_e32 v25, v25, v26
	global_store_dword v[28:29], v25, off offset:16

.LBB0_501:
	s_and_b64 s[0:1], s[84:85], exec
	s_cselect_b32 s1, s79, s87
	s_cselect_b32 s0, s78, s86
	v_lshlrev_b64 v[18:19], 10, v[18:19]
	v_lshl_add_u64 v[18:19], s[0:1], 0, v[18:19]
	s_lshl_b32 s26, s69, 1
	v_lshl_add_u64 v[18:19], v[18:19], 0, s[26:27]
	s_lshl_b32 s26, s88, 1
	v_lshl_add_u64 v[18:19], v[18:19], 0, s[26:27]
	v_lshlrev_b32_e32 v134, 1, v136
	v_lshl_add_u64 v[18:19], v[18:19], 0, v[134:135]
	s_and_b64 vcc, exec, s[8:9]
	v_cvt_pk_bf16_f32 v14, v14, v15
	v_cvt_pk_bf16_f32 v15, v16, v17
	v_mov_b32_e32 v246, v14
	v_mov_b32_e32 v247, v15
	s_cbranch_vccnz .LBB0_503
	v_mul_f32_e32 v15, 0x3d372713, v11
	v_mov_b32_e32 v16, v11
	v_mul_f32_e32 v15, v11, v15
	v_fmac_f32_e32 v16, v16, v15
	v_mul_f32_e32 v14, 0x3d372713, v10
	v_mul_f32_e32 v15, 0x3f4c422a, v16
	v_mul_f32_e32 v16, 0x3d372713, v12
	v_mul_f32_e32 v17, 0x3d372713, v13
	v_mul_f32_e32 v14, v10, v14
	v_mul_f32_e32 v16, v12, v16
	v_mul_f32_e32 v17, v13, v17
	v_fma_f32 v14, v10, v14, v10
	v_fma_f32 v16, v12, v16, v12
	v_fma_f32 v17, v13, v17, v13
	v_mul_f32_e32 v14, 0x3f4c422a, v14
	v_mul_f32_e32 v16, 0x3f4c422a, v16
	v_mul_f32_e32 v17, 0x3f4c422a, v17
	v_mul_f32_e32 v14, 0xc038aa3b, v14
	v_mul_f32_e32 v15, 0xc038aa3b, v15
	v_mul_f32_e32 v16, 0xc038aa3b, v16
	v_mul_f32_e32 v17, 0xc038aa3b, v17
	v_exp_f32_e32 v14, v14
	v_exp_f32_e32 v15, v15
	v_exp_f32_e32 v16, v16
	v_exp_f32_e32 v17, v17
	v_add_f32_e32 v14, 1.0, v14
	v_add_f32_e32 v15, 1.0, v15
	v_add_f32_e32 v16, 1.0, v16
	v_add_f32_e32 v17, 1.0, v17
	v_rcp_f32_e32 v14, v14
	v_rcp_f32_e32 v16, v16
	v_rcp_f32_e32 v17, v17
	v_rcp_f32_e32 v15, v15
	v_pk_mul_f32 v[12:13], v[12:13], v[16:17]
	v_pk_mul_f32 v[10:11], v[10:11], v[14:15]
.LBB0_503:
	s_and_b64 vcc, exec, s[8:9]
	v_cvt_pk_bf16_f32 v10, v10, v11
	v_cvt_pk_bf16_f32 v11, v12, v13
	v_mov_b32_e32 v248, v10
	v_mov_b32_e32 v249, v11
	s_nop 1
	v_permlane16_swap_b32_e32 v246, v248
	v_permlane16_swap_b32_e32 v247, v249
	v_lshl_add_u64 v[252:253], v[18:19], 0, v[250:251]
	global_store_dwordx4 v[252:253], v[246:249], off
	s_nop 0
	s_cbranch_vccnz .LBB0_505
	v_mul_f32_e32 v11, 0x3d372713, v7
	v_mov_b32_e32 v12, v7
	v_mul_f32_e32 v11, v7, v11
	v_fmac_f32_e32 v12, v12, v11
	v_mul_f32_e32 v10, 0x3d372713, v6
	v_mul_f32_e32 v11, 0x3f4c422a, v12
	v_mul_f32_e32 v12, 0x3d372713, v8
	v_mul_f32_e32 v13, 0x3d372713, v9
	v_mul_f32_e32 v10, v6, v10
	v_mul_f32_e32 v12, v8, v12
	v_mul_f32_e32 v13, v9, v13
	v_fma_f32 v10, v6, v10, v6
	v_fma_f32 v12, v8, v12, v8
	v_fma_f32 v13, v9, v13, v9
	v_mul_f32_e32 v10, 0x3f4c422a, v10
	v_mul_f32_e32 v12, 0x3f4c422a, v12
	v_mul_f32_e32 v13, 0x3f4c422a, v13
	v_mul_f32_e32 v10, 0xc038aa3b, v10
	v_mul_f32_e32 v11, 0xc038aa3b, v11
	v_mul_f32_e32 v12, 0xc038aa3b, v12
	v_mul_f32_e32 v13, 0xc038aa3b, v13
	v_exp_f32_e32 v10, v10
	v_exp_f32_e32 v11, v11
	v_exp_f32_e32 v12, v12
	v_exp_f32_e32 v13, v13
	v_add_f32_e32 v10, 1.0, v10
	v_add_f32_e32 v11, 1.0, v11
	v_add_f32_e32 v12, 1.0, v12
	v_add_f32_e32 v13, 1.0, v13
	v_rcp_f32_e32 v10, v10
	v_rcp_f32_e32 v12, v12
	v_rcp_f32_e32 v13, v13
	v_rcp_f32_e32 v11, v11
	v_pk_mul_f32 v[8:9], v[8:9], v[12:13]
	v_pk_mul_f32 v[6:7], v[6:7], v[10:11]
.LBB0_505:
	s_and_b64 vcc, exec, s[8:9]
	v_cvt_pk_bf16_f32 v6, v6, v7
	v_cvt_pk_bf16_f32 v7, v8, v9
	v_mov_b32_e32 v246, v6
	v_mov_b32_e32 v247, v7
	s_cbranch_vccnz .LBB0_507
	v_mul_f32_e32 v7, 0x3d372713, v3
	v_mov_b32_e32 v8, v3
	v_mul_f32_e32 v7, v3, v7
	v_fmac_f32_e32 v8, v8, v7
	v_mul_f32_e32 v6, 0x3d372713, v2
	v_mul_f32_e32 v7, 0x3f4c422a, v8
	v_mul_f32_e32 v8, 0x3d372713, v4
	v_mul_f32_e32 v9, 0x3d372713, v5
	v_mul_f32_e32 v6, v2, v6
	v_mul_f32_e32 v8, v4, v8
	v_mul_f32_e32 v9, v5, v9
	v_fma_f32 v6, v2, v6, v2
	v_fma_f32 v8, v4, v8, v4
	v_fma_f32 v9, v5, v9, v5
	v_mul_f32_e32 v6, 0x3f4c422a, v6
	v_mul_f32_e32 v8, 0x3f4c422a, v8
	v_mul_f32_e32 v9, 0x3f4c422a, v9
	v_mul_f32_e32 v6, 0xc038aa3b, v6
	v_mul_f32_e32 v7, 0xc038aa3b, v7
	v_mul_f32_e32 v8, 0xc038aa3b, v8
	v_mul_f32_e32 v9, 0xc038aa3b, v9
	v_exp_f32_e32 v6, v6
	v_exp_f32_e32 v7, v7
	v_exp_f32_e32 v8, v8
	v_exp_f32_e32 v9, v9
	v_add_f32_e32 v6, 1.0, v6
	v_add_f32_e32 v7, 1.0, v7
	v_add_f32_e32 v8, 1.0, v8
	v_add_f32_e32 v9, 1.0, v9
	v_rcp_f32_e32 v6, v6
	v_rcp_f32_e32 v8, v8
	v_rcp_f32_e32 v9, v9
	v_rcp_f32_e32 v7, v7
	v_pk_mul_f32 v[4:5], v[4:5], v[8:9]
	v_pk_mul_f32 v[2:3], v[2:3], v[6:7]
.LBB0_507:
	s_nop 0
	v_cvt_pk_bf16_f32 v2, v2, v3
	v_cvt_pk_bf16_f32 v3, v4, v5
	v_mov_b32_e32 v248, v2
	v_mov_b32_e32 v249, v3
	s_nop 1
	v_permlane16_swap_b32_e32 v246, v248
	v_permlane16_swap_b32_e32 v247, v249
	v_lshl_add_u64 v[252:253], v[18:19], 0, v[250:251]
	global_store_dwordx4 v[252:253], v[246:249], off offset:256
	s_nop 0
	s_andn2_b64 vcc, exec, s[6:7]
	s_mov_b64 s[6:7], -1
	s_cbranch_vccnz .LBB0_324
